# smp_ssd epilogue: z rows of the 4 tokens requested up front (dummy loads), on top of q0 idle-slot conversion
# baseline (speedup 1.0000x reference)
.LBB0_359:
	s_andn2_saveexec_b64 s[2:3], s[2:3]
	v_mov_b32_e32 v1, 0
	s_or_b64 exec, exec, s[2:3]
	v_lshl_add_u32 v88, s70, 3, v0
	v_ashrrev_i32_e32 v89, 31, v88
	v_lshlrev_b64 v[2:3], 13, v[88:89]
	v_lshl_add_u32 v89, v0, 2, 0
	ds_write_b32 v91, v1 offset:37888
	s_waitcnt lgkmcnt(0)
	s_barrier
	ds_read_b32 v0, v89 offset:37632
	s_lshl_b64 s[2:3], s[4:5], 17
	v_lshl_add_u64 v[2:3], v[2:3], 0, s[2:3]
	v_and_b32_e32 v106, 15, v97
	v_lshlrev_b64 v[2:3], 2, v[2:3]
	v_bfe_u32 v105, v97, 4, 2
	v_lshl_add_u64 v[84:85], s[22:23], 0, v[2:3]
	v_lshlrev_b32_e32 v168, 9, v106
	s_waitcnt lgkmcnt(0)
	v_mul_f32_e32 v6, 0x3fb8aa3b, v0
	v_lshl_add_u64 v[0:1], v[84:85], 0, v[168:169]
	v_lshlrev_b32_e32 v92, 5, v105
	v_mov_b32_e32 v93, v169
	v_lshl_add_u64 v[4:5], v[0:1], 0, v[92:93]
	global_load_dwordx4 v[74:77], v[4:5], off offset:16 nt
	global_load_dwordx4 v[78:81], v[4:5], off nt
	global_load_dwordx4 v[48:51], v[4:5], off offset:144 nt
	global_load_dwordx4 v[60:63], v[4:5], off offset:128 nt
	global_load_dwordx4 v[32:35], v[4:5], off offset:272 nt
	global_load_dwordx4 v[44:47], v[4:5], off offset:256 nt
	global_load_dwordx4 v[16:19], v[4:5], off offset:400 nt
	global_load_dwordx4 v[28:31], v[4:5], off offset:384 nt
	v_readlane_b32 s2, v240, 40
	v_readlane_b32 s3, v240, 41
	v_lshlrev_b32_e32 v108, 5, v97
	v_mul_u32_u24_e32 v68, 0x110, v106
	v_lshl_add_u64 v[94:95], s[2:3], 0, v[2:3]
	s_mov_b64 s[2:3], 0x2000
	v_and_b32_e32 v0, 0xfffff9e0, v108
	v_lshl_add_u64 v[8:9], v[4:5], 0, s[2:3]
	v_add_co_u32_e32 v4, vcc, s75, v4
	v_lshlrev_b32_e32 v69, 4, v105
	v_add_u32_e32 v0, 0, v0
	v_addc_co_u32_e32 v5, vcc, 0, v5, vcc
	v_add3_u32 v112, 0, v68, v69
	v_add_u32_e32 v111, 0, v92
	v_exp_f32_e32 v90, v6
	ds_read_b128 v[12:15], v0 offset:16384
	ds_read_b128 v[0:3], v0 offset:16400
	global_load_dwordx4 v[56:59], v[4:5], off nt
	global_load_dwordx4 v[52:55], v[8:9], off offset:16 nt
	global_load_dwordx4 v[36:39], v[8:9], off offset:144 nt
	global_load_dwordx4 v[40:43], v[8:9], off offset:128 nt
	global_load_dwordx4 v[20:23], v[8:9], off offset:272 nt
	global_load_dwordx4 v[24:27], v[8:9], off offset:256 nt
	global_load_dwordx4 v[4:7], v[8:9], off offset:400 nt
	s_nop 0
	global_load_dwordx4 v[8:11], v[8:9], off offset:384 nt
	ds_read_b128 v[68:71], v112 offset:40448
	ds_read_b128 v[98:101], v111 offset:32768
	ds_read_b128 v[114:117], v111 offset:32784
	v_lshl_add_u64 v[72:73], v[94:95], 0, v[168:169]
	v_and_b32_e32 v107, 0xffffffc0, v97
	v_readlane_b32 s36, v241, 27
	s_waitcnt lgkmcnt(1)
	v_pk_mul_f32 v[82:83], v[12:13], v[98:99] op_sel_hi:[0,1]
	v_pk_mul_f32 v[86:87], v[12:13], v[100:101] op_sel_hi:[0,1]
	v_readlane_b32 s37, v241, 28
	s_or_b32 s8, s69, 0x1000
	v_readlane_b32 s38, v241, 29
	v_readlane_b32 s39, v241, 30
	v_readlane_b32 s40, v241, 31
	v_readlane_b32 s41, v241, 32
	v_readlane_b32 s42, v241, 33
	v_readlane_b32 s43, v241, 34
	v_readlane_b32 s44, v241, 35
	v_readlane_b32 s45, v241, 36
	v_readlane_b32 s46, v241, 37
	v_readlane_b32 s47, v241, 38
	v_readlane_b32 s48, v241, 39
	v_readlane_b32 s49, v241, 40
	v_readlane_b32 s50, v241, 41
	v_readlane_b32 s51, v241, 42
	s_waitcnt vmcnt(15)
	v_cvt_pk_bf16_f32 v66, v74, v75
	s_waitcnt vmcnt(14)
	v_cvt_pk_bf16_f32 v64, v78, v79
	v_cvt_pk_bf16_f32 v65, v80, v81
	v_pk_fma_f32 v[86:87], v[80:81], v[90:91], v[86:87] op_sel_hi:[1,0,1]
	v_pk_fma_f32 v[82:83], v[78:79], v[90:91], v[82:83] op_sel_hi:[1,0,1]
	s_waitcnt lgkmcnt(0)
	v_pk_mul_f32 v[78:79], v[12:13], v[114:115] op_sel_hi:[0,1]
	v_pk_mul_f32 v[80:81], v[12:13], v[116:117] op_sel_hi:[0,1]
	v_cvt_pk_bf16_f32 v67, v76, v77
	v_pk_fma_f32 v[98:99], v[76:77], v[90:91], v[80:81] op_sel_hi:[1,0,1]
	v_pk_fma_f32 v[100:101], v[74:75], v[90:91], v[78:79] op_sel_hi:[1,0,1]
	ds_read_b128 v[74:77], v111 offset:33280
	ds_read_b128 v[78:81], v111 offset:33296
	v_mfma_f32_16x16x32_bf16 v[64:67], v[68:71], v[64:67], 0
	s_waitcnt vmcnt(12)
	v_cvt_pk_bf16_f32 v68, v60, v61
	v_cvt_pk_bf16_f32 v69, v62, v63
	s_waitcnt lgkmcnt(1)
	v_pk_fma_f32 v[86:87], v[12:13], v[76:77], v[86:87] op_sel:[1,0,0]
	v_pk_fma_f32 v[82:83], v[12:13], v[74:75], v[82:83] op_sel:[1,0,0]
	s_waitcnt lgkmcnt(0)
	v_pk_fma_f32 v[98:99], v[12:13], v[80:81], v[98:99] op_sel:[1,0,0]
	v_pk_fma_f32 v[100:101], v[12:13], v[78:79], v[100:101] op_sel:[1,0,0]
	ds_read_b128 v[74:77], v111 offset:33792
	ds_read_b128 v[78:81], v111 offset:33808
	v_cvt_pk_bf16_f32 v70, v48, v49
	v_cvt_pk_bf16_f32 v71, v50, v51
	s_waitcnt lgkmcnt(1)
	v_pk_fma_f32 v[74:75], v[14:15], v[74:75], v[82:83] op_sel_hi:[0,1,1]
	s_waitcnt lgkmcnt(0)
	v_pk_fma_f32 v[82:83], v[14:15], v[80:81], v[98:99] op_sel_hi:[0,1,1]
	v_pk_fma_f32 v[114:115], v[14:15], v[78:79], v[100:101] op_sel_hi:[0,1,1]
	ds_read_b128 v[78:81], v111 offset:34304
	ds_read_b128 v[98:101], v111 offset:34320
	v_pk_fma_f32 v[86:87], v[14:15], v[76:77], v[86:87] op_sel_hi:[0,1,1]
	v_mov_b32_e32 v76, v15
	s_waitcnt lgkmcnt(1)
	v_pk_fma_f32 v[86:87], v[76:77], v[80:81], v[86:87] op_sel_hi:[0,1,1]
	v_pk_fma_f32 v[74:75], v[76:77], v[78:79], v[74:75] op_sel_hi:[0,1,1]
	s_waitcnt lgkmcnt(0)
	v_pk_fma_f32 v[82:83], v[76:77], v[100:101], v[82:83] op_sel_hi:[0,1,1]
	v_pk_fma_f32 v[114:115], v[76:77], v[98:99], v[114:115] op_sel_hi:[0,1,1]
	ds_read_b128 v[78:81], v111 offset:34816
	ds_read_b128 v[98:101], v111 offset:34832
	s_waitcnt lgkmcnt(1)
	v_pk_fma_f32 v[86:87], v[0:1], v[80:81], v[86:87] op_sel_hi:[0,1,1]
	v_pk_fma_f32 v[74:75], v[0:1], v[78:79], v[74:75] op_sel_hi:[0,1,1]
	s_waitcnt lgkmcnt(0)
	v_pk_fma_f32 v[82:83], v[0:1], v[100:101], v[82:83] op_sel_hi:[0,1,1]
	v_pk_fma_f32 v[114:115], v[0:1], v[98:99], v[114:115] op_sel_hi:[0,1,1]
	ds_read_b128 v[78:81], v111 offset:35328
	ds_read_b128 v[98:101], v111 offset:35344
	s_waitcnt lgkmcnt(1)
	v_pk_fma_f32 v[86:87], v[0:1], v[80:81], v[86:87] op_sel:[1,0,0]
	v_pk_fma_f32 v[74:75], v[0:1], v[78:79], v[74:75] op_sel:[1,0,0]
	s_waitcnt lgkmcnt(0)
	v_pk_fma_f32 v[82:83], v[0:1], v[100:101], v[82:83] op_sel:[1,0,0]
	v_pk_fma_f32 v[114:115], v[0:1], v[98:99], v[114:115] op_sel:[1,0,0]
	ds_read_b128 v[78:81], v111 offset:35840
	ds_read_b128 v[98:101], v111 offset:35856
	s_waitcnt lgkmcnt(1)
	v_pk_fma_f32 v[74:75], v[2:3], v[78:79], v[74:75] op_sel_hi:[0,1,1]
	s_waitcnt lgkmcnt(0)
	v_pk_fma_f32 v[78:79], v[2:3], v[100:101], v[82:83] op_sel_hi:[0,1,1]
	v_pk_fma_f32 v[82:83], v[2:3], v[98:99], v[114:115] op_sel_hi:[0,1,1]
	ds_read_b128 v[98:101], v111 offset:36352
	ds_read_b128 v[114:117], v111 offset:36368
	v_pk_fma_f32 v[86:87], v[2:3], v[80:81], v[86:87] op_sel_hi:[0,1,1]
	v_mov_b32_e32 v80, v3
	s_waitcnt lgkmcnt(1)
	v_pk_fma_f32 v[100:101], v[80:81], v[100:101], v[86:87] op_sel_hi:[0,1,1]
	v_pk_fma_f32 v[98:99], v[80:81], v[98:99], v[74:75] op_sel_hi:[0,1,1]
	s_waitcnt lgkmcnt(0)
	v_pk_fma_f32 v[116:117], v[80:81], v[116:117], v[78:79] op_sel_hi:[0,1,1]
	v_lshl_add_u64 v[78:79], v[72:73], 0, v[92:93]
	v_pk_fma_f32 v[114:115], v[80:81], v[114:115], v[82:83] op_sel_hi:[0,1,1]
	global_store_dwordx4 v[78:79], v[98:101], off nt
	global_store_dwordx4 v[78:79], v[114:117], off offset:16 nt
	ds_read_b128 v[72:75], v112 offset:40512
	ds_read_b128 v[98:101], v111 offset:32896
	ds_read_b128 v[114:117], v111 offset:32912
	s_waitcnt lgkmcnt(1)
	v_pk_mul_f32 v[82:83], v[12:13], v[98:99] op_sel_hi:[0,1]
	v_pk_mul_f32 v[86:87], v[12:13], v[100:101] op_sel_hi:[0,1]
	v_pk_fma_f32 v[86:87], v[62:63], v[90:91], v[86:87] op_sel_hi:[1,0,1]
	v_pk_fma_f32 v[82:83], v[60:61], v[90:91], v[82:83] op_sel_hi:[1,0,1]
	s_waitcnt lgkmcnt(0)
	v_pk_mul_f32 v[60:61], v[12:13], v[114:115] op_sel_hi:[0,1]
	v_pk_mul_f32 v[62:63], v[12:13], v[116:117] op_sel_hi:[0,1]
	v_pk_fma_f32 v[98:99], v[90:91], v[50:51], v[62:63] op_sel_hi:[0,1,1]
	v_pk_fma_f32 v[100:101], v[90:91], v[48:49], v[60:61] op_sel_hi:[0,1,1]
	ds_read_b128 v[48:51], v111 offset:33408
	ds_read_b128 v[60:63], v111 offset:33424
	s_waitcnt lgkmcnt(1)
	v_pk_fma_f32 v[86:87], v[12:13], v[50:51], v[86:87] op_sel:[1,0,0]
	v_pk_fma_f32 v[82:83], v[12:13], v[48:49], v[82:83] op_sel:[1,0,0]
	s_waitcnt lgkmcnt(0)
	v_pk_fma_f32 v[98:99], v[12:13], v[62:63], v[98:99] op_sel:[1,0,0]
	v_pk_fma_f32 v[100:101], v[12:13], v[60:61], v[100:101] op_sel:[1,0,0]
	ds_read_b128 v[48:51], v111 offset:33920
	ds_read_b128 v[60:63], v111 offset:33936
	s_waitcnt lgkmcnt(1)
	v_pk_fma_f32 v[86:87], v[14:15], v[50:51], v[86:87] op_sel_hi:[0,1,1]
	v_pk_fma_f32 v[82:83], v[14:15], v[48:49], v[82:83] op_sel_hi:[0,1,1]
	s_waitcnt lgkmcnt(0)
	v_pk_fma_f32 v[98:99], v[14:15], v[62:63], v[98:99] op_sel_hi:[0,1,1]
	v_pk_fma_f32 v[100:101], v[14:15], v[60:61], v[100:101] op_sel_hi:[0,1,1]
	ds_read_b128 v[48:51], v111 offset:34432
	ds_read_b128 v[60:63], v111 offset:34448
	s_waitcnt lgkmcnt(1)
	v_pk_fma_f32 v[86:87], v[76:77], v[50:51], v[86:87] op_sel_hi:[0,1,1]
	v_pk_fma_f32 v[82:83], v[76:77], v[48:49], v[82:83] op_sel_hi:[0,1,1]
	s_waitcnt lgkmcnt(0)
	v_pk_fma_f32 v[98:99], v[76:77], v[62:63], v[98:99] op_sel_hi:[0,1,1]
	v_pk_fma_f32 v[100:101], v[76:77], v[60:61], v[100:101] op_sel_hi:[0,1,1]
	ds_read_b128 v[48:51], v111 offset:34944
	ds_read_b128 v[60:63], v111 offset:34960
	s_waitcnt lgkmcnt(1)
	v_pk_fma_f32 v[86:87], v[0:1], v[50:51], v[86:87] op_sel_hi:[0,1,1]
	v_pk_fma_f32 v[82:83], v[0:1], v[48:49], v[82:83] op_sel_hi:[0,1,1]
	s_waitcnt lgkmcnt(0)
	v_pk_fma_f32 v[98:99], v[0:1], v[62:63], v[98:99] op_sel_hi:[0,1,1]
	v_pk_fma_f32 v[100:101], v[0:1], v[60:61], v[100:101] op_sel_hi:[0,1,1]
	ds_read_b128 v[48:51], v111 offset:35456
	ds_read_b128 v[60:63], v111 offset:35472
	s_waitcnt lgkmcnt(1)
	v_pk_fma_f32 v[86:87], v[0:1], v[50:51], v[86:87] op_sel:[1,0,0]
	v_pk_fma_f32 v[82:83], v[0:1], v[48:49], v[82:83] op_sel:[1,0,0]
	s_waitcnt lgkmcnt(0)
	v_pk_fma_f32 v[98:99], v[0:1], v[62:63], v[98:99] op_sel:[1,0,0]
	v_pk_fma_f32 v[100:101], v[0:1], v[60:61], v[100:101] op_sel:[1,0,0]
	ds_read_b128 v[48:51], v111 offset:35968
	ds_read_b128 v[60:63], v111 offset:35984
	s_waitcnt lgkmcnt(1)
	v_pk_fma_f32 v[86:87], v[2:3], v[50:51], v[86:87] op_sel_hi:[0,1,1]
	v_pk_fma_f32 v[82:83], v[2:3], v[48:49], v[82:83] op_sel_hi:[0,1,1]
	s_waitcnt lgkmcnt(0)
	v_pk_fma_f32 v[114:115], v[2:3], v[62:63], v[98:99] op_sel_hi:[0,1,1]
	v_pk_fma_f32 v[116:117], v[2:3], v[60:61], v[100:101] op_sel_hi:[0,1,1]
	ds_read_b128 v[48:51], v111 offset:36480
	ds_read_b128 v[60:63], v111 offset:36496
	s_waitcnt lgkmcnt(1)
	v_pk_fma_f32 v[100:101], v[80:81], v[50:51], v[86:87] op_sel_hi:[0,1,1]
	v_pk_fma_f32 v[98:99], v[80:81], v[48:49], v[82:83] op_sel_hi:[0,1,1]
	s_waitcnt lgkmcnt(0)
	v_pk_fma_f32 v[62:63], v[80:81], v[62:63], v[114:115] op_sel_hi:[0,1,1]
	v_pk_fma_f32 v[60:61], v[80:81], v[60:61], v[116:117] op_sel_hi:[0,1,1]
	global_store_dwordx4 v[78:79], v[98:101], off offset:128 nt
	global_store_dwordx4 v[78:79], v[60:63], off offset:144 nt
	v_mfma_f32_16x16x32_bf16 v[48:51], v[72:75], v[68:71], v[64:67]
	s_nop 2
	ds_read_b128 v[64:67], v112 offset:40576
	ds_read_b128 v[68:71], v111 offset:33024
	ds_read_b128 v[72:75], v111 offset:33040
	s_waitcnt vmcnt(14)
	v_cvt_pk_bf16_f32 v60, v44, v45
	v_cvt_pk_bf16_f32 v61, v46, v47
	v_cvt_pk_bf16_f32 v62, v32, v33
	s_waitcnt lgkmcnt(1)
	v_pk_mul_f32 v[68:69], v[12:13], v[68:69] op_sel_hi:[0,1]
	v_pk_mul_f32 v[70:71], v[12:13], v[70:71] op_sel_hi:[0,1]
	v_pk_fma_f32 v[70:71], v[90:91], v[46:47], v[70:71] op_sel_hi:[0,1,1]
	v_pk_fma_f32 v[68:69], v[90:91], v[44:45], v[68:69] op_sel_hi:[0,1,1]
	s_waitcnt lgkmcnt(0)
	v_pk_mul_f32 v[44:45], v[12:13], v[72:73] op_sel_hi:[0,1]
	v_pk_mul_f32 v[46:47], v[12:13], v[74:75] op_sel_hi:[0,1]
	v_cvt_pk_bf16_f32 v63, v34, v35
	v_pk_fma_f32 v[72:73], v[90:91], v[34:35], v[46:47] op_sel_hi:[0,1,1]
	v_pk_fma_f32 v[74:75], v[90:91], v[32:33], v[44:45] op_sel_hi:[0,1,1]
	ds_read_b128 v[32:35], v111 offset:33536
	ds_read_b128 v[44:47], v111 offset:33552
	s_waitcnt lgkmcnt(1)
	v_pk_fma_f32 v[70:71], v[12:13], v[34:35], v[70:71] op_sel:[1,0,0]
	v_pk_fma_f32 v[68:69], v[12:13], v[32:33], v[68:69] op_sel:[1,0,0]
	s_waitcnt lgkmcnt(0)
	v_pk_fma_f32 v[72:73], v[12:13], v[46:47], v[72:73] op_sel:[1,0,0]
	v_pk_fma_f32 v[74:75], v[12:13], v[44:45], v[74:75] op_sel:[1,0,0]
	ds_read_b128 v[32:35], v111 offset:34048
	ds_read_b128 v[44:47], v111 offset:34064
	s_waitcnt lgkmcnt(1)
	v_pk_fma_f32 v[70:71], v[14:15], v[34:35], v[70:71] op_sel_hi:[0,1,1]
	v_pk_fma_f32 v[68:69], v[14:15], v[32:33], v[68:69] op_sel_hi:[0,1,1]
	s_waitcnt lgkmcnt(0)
	v_pk_fma_f32 v[72:73], v[14:15], v[46:47], v[72:73] op_sel_hi:[0,1,1]
	v_pk_fma_f32 v[74:75], v[14:15], v[44:45], v[74:75] op_sel_hi:[0,1,1]
	ds_read_b128 v[32:35], v111 offset:34560
	ds_read_b128 v[44:47], v111 offset:34576
	s_waitcnt lgkmcnt(1)
	v_pk_fma_f32 v[70:71], v[76:77], v[34:35], v[70:71] op_sel_hi:[0,1,1]
	v_pk_fma_f32 v[68:69], v[76:77], v[32:33], v[68:69] op_sel_hi:[0,1,1]
	s_waitcnt lgkmcnt(0)
	v_pk_fma_f32 v[72:73], v[76:77], v[46:47], v[72:73] op_sel_hi:[0,1,1]
	v_pk_fma_f32 v[74:75], v[76:77], v[44:45], v[74:75] op_sel_hi:[0,1,1]
	ds_read_b128 v[32:35], v111 offset:35072
	ds_read_b128 v[44:47], v111 offset:35088
	s_waitcnt lgkmcnt(1)
	v_pk_fma_f32 v[70:71], v[0:1], v[34:35], v[70:71] op_sel_hi:[0,1,1]
	v_pk_fma_f32 v[68:69], v[0:1], v[32:33], v[68:69] op_sel_hi:[0,1,1]
	s_waitcnt lgkmcnt(0)
	v_pk_fma_f32 v[72:73], v[0:1], v[46:47], v[72:73] op_sel_hi:[0,1,1]
	v_pk_fma_f32 v[74:75], v[0:1], v[44:45], v[74:75] op_sel_hi:[0,1,1]
	ds_read_b128 v[32:35], v111 offset:35584
	ds_read_b128 v[44:47], v111 offset:35600
	s_waitcnt lgkmcnt(1)
	v_pk_fma_f32 v[70:71], v[0:1], v[34:35], v[70:71] op_sel:[1,0,0]
	v_pk_fma_f32 v[68:69], v[0:1], v[32:33], v[68:69] op_sel:[1,0,0]
	s_waitcnt lgkmcnt(0)
	v_pk_fma_f32 v[72:73], v[0:1], v[46:47], v[72:73] op_sel:[1,0,0]
	v_pk_fma_f32 v[74:75], v[0:1], v[44:45], v[74:75] op_sel:[1,0,0]
	ds_read_b128 v[32:35], v111 offset:36096
	ds_read_b128 v[44:47], v111 offset:36112
	s_waitcnt lgkmcnt(1)
	v_pk_fma_f32 v[70:71], v[2:3], v[34:35], v[70:71] op_sel_hi:[0,1,1]
	v_pk_fma_f32 v[68:69], v[2:3], v[32:33], v[68:69] op_sel_hi:[0,1,1]
	s_waitcnt lgkmcnt(0)
	v_pk_fma_f32 v[72:73], v[2:3], v[46:47], v[72:73] op_sel_hi:[0,1,1]
	v_pk_fma_f32 v[74:75], v[2:3], v[44:45], v[74:75] op_sel_hi:[0,1,1]
	ds_read_b128 v[32:35], v111 offset:36608
	ds_read_b128 v[44:47], v111 offset:36624
	s_waitcnt lgkmcnt(1)
	v_pk_fma_f32 v[70:71], v[80:81], v[34:35], v[70:71] op_sel_hi:[0,1,1]
	v_pk_fma_f32 v[68:69], v[80:81], v[32:33], v[68:69] op_sel_hi:[0,1,1]
	s_waitcnt lgkmcnt(0)
	v_pk_fma_f32 v[46:47], v[80:81], v[46:47], v[72:73] op_sel_hi:[0,1,1]
	v_pk_fma_f32 v[44:45], v[80:81], v[44:45], v[74:75] op_sel_hi:[0,1,1]
	global_store_dwordx4 v[78:79], v[68:71], off offset:256 nt
	global_store_dwordx4 v[78:79], v[44:47], off offset:272 nt
	v_mfma_f32_16x16x32_bf16 v[32:35], v[64:67], v[60:63], v[48:51]
	s_nop 2
	ds_read_b128 v[48:51], v112 offset:40640
	ds_read_b128 v[60:63], v111 offset:33152
	ds_read_b128 v[64:67], v111 offset:33168
	s_waitcnt vmcnt(14)
	v_cvt_pk_bf16_f32 v44, v28, v29
	v_cvt_pk_bf16_f32 v45, v30, v31
	v_cvt_pk_bf16_f32 v46, v16, v17
	s_waitcnt lgkmcnt(1)
	v_pk_mul_f32 v[60:61], v[12:13], v[60:61] op_sel_hi:[0,1]
	v_pk_mul_f32 v[62:63], v[12:13], v[62:63] op_sel_hi:[0,1]
	v_pk_fma_f32 v[62:63], v[90:91], v[30:31], v[62:63] op_sel_hi:[0,1,1]
	v_pk_fma_f32 v[60:61], v[90:91], v[28:29], v[60:61] op_sel_hi:[0,1,1]
	s_waitcnt lgkmcnt(0)
	v_pk_mul_f32 v[28:29], v[12:13], v[64:65] op_sel_hi:[0,1]
	v_pk_mul_f32 v[30:31], v[12:13], v[66:67] op_sel_hi:[0,1]
	v_cvt_pk_bf16_f32 v47, v18, v19
	v_pk_fma_f32 v[64:65], v[90:91], v[18:19], v[30:31] op_sel_hi:[0,1,1]
	v_pk_fma_f32 v[66:67], v[90:91], v[16:17], v[28:29] op_sel_hi:[0,1,1]
	ds_read_b128 v[16:19], v111 offset:33664
	ds_read_b128 v[28:31], v111 offset:33680
	s_waitcnt lgkmcnt(1)
	v_pk_fma_f32 v[62:63], v[12:13], v[18:19], v[62:63] op_sel:[1,0,0]
	v_pk_fma_f32 v[60:61], v[12:13], v[16:17], v[60:61] op_sel:[1,0,0]
	s_waitcnt lgkmcnt(0)
	v_pk_fma_f32 v[64:65], v[12:13], v[30:31], v[64:65] op_sel:[1,0,0]
	v_pk_fma_f32 v[12:13], v[12:13], v[28:29], v[66:67] op_sel:[1,0,0]
	ds_read_b128 v[16:19], v111 offset:34176
	ds_read_b128 v[28:31], v111 offset:34192
	s_waitcnt lgkmcnt(1)
	v_pk_fma_f32 v[62:63], v[14:15], v[18:19], v[62:63] op_sel_hi:[0,1,1]
	v_pk_fma_f32 v[60:61], v[14:15], v[16:17], v[60:61] op_sel_hi:[0,1,1]
	s_waitcnt lgkmcnt(0)
	v_pk_fma_f32 v[30:31], v[14:15], v[30:31], v[64:65] op_sel_hi:[0,1,1]
	v_pk_fma_f32 v[28:29], v[14:15], v[28:29], v[12:13] op_sel_hi:[0,1,1]
	ds_read_b128 v[12:15], v111 offset:34688
	ds_read_b128 v[16:19], v111 offset:34704
	s_waitcnt lgkmcnt(1)
	v_pk_fma_f32 v[62:63], v[76:77], v[14:15], v[62:63] op_sel_hi:[0,1,1]
	v_pk_fma_f32 v[60:61], v[76:77], v[12:13], v[60:61] op_sel_hi:[0,1,1]
	s_waitcnt lgkmcnt(0)
	v_pk_fma_f32 v[30:31], v[76:77], v[18:19], v[30:31] op_sel_hi:[0,1,1]
	v_pk_fma_f32 v[28:29], v[76:77], v[16:17], v[28:29] op_sel_hi:[0,1,1]
	ds_read_b128 v[12:15], v111 offset:35200
	ds_read_b128 v[16:19], v111 offset:35216
	s_waitcnt vmcnt(13)
	v_cvt_pk_bf16_f32 v76, v56, v57
	v_cvt_pk_bf16_f32 v77, v58, v59
	s_waitcnt lgkmcnt(1)
	v_pk_fma_f32 v[62:63], v[0:1], v[14:15], v[62:63] op_sel_hi:[0,1,1]
	v_pk_fma_f32 v[60:61], v[0:1], v[12:13], v[60:61] op_sel_hi:[0,1,1]
	s_waitcnt lgkmcnt(0)
	v_pk_fma_f32 v[30:31], v[0:1], v[18:19], v[30:31] op_sel_hi:[0,1,1]
	v_pk_fma_f32 v[28:29], v[0:1], v[16:17], v[28:29] op_sel_hi:[0,1,1]
	ds_read_b128 v[12:15], v111 offset:35712
	ds_read_b128 v[16:19], v111 offset:35728
	s_waitcnt lgkmcnt(1)
	v_pk_fma_f32 v[62:63], v[0:1], v[14:15], v[62:63] op_sel:[1,0,0]
	v_pk_fma_f32 v[60:61], v[0:1], v[12:13], v[60:61] op_sel:[1,0,0]
	s_waitcnt lgkmcnt(0)
	v_pk_fma_f32 v[30:31], v[0:1], v[18:19], v[30:31] op_sel:[1,0,0]
	v_pk_fma_f32 v[0:1], v[0:1], v[16:17], v[28:29] op_sel:[1,0,0]
	ds_read_b128 v[12:15], v111 offset:36224
	ds_read_b128 v[16:19], v111 offset:36240
	s_waitcnt lgkmcnt(1)
	v_pk_fma_f32 v[28:29], v[2:3], v[14:15], v[62:63] op_sel_hi:[0,1,1]
	v_pk_fma_f32 v[60:61], v[2:3], v[12:13], v[60:61] op_sel_hi:[0,1,1]
	s_waitcnt lgkmcnt(0)
	v_pk_fma_f32 v[30:31], v[2:3], v[18:19], v[30:31] op_sel_hi:[0,1,1]
	v_pk_fma_f32 v[62:63], v[2:3], v[16:17], v[0:1] op_sel_hi:[0,1,1]
	ds_read_b128 v[0:3], v111 offset:36736
	ds_read_b128 v[12:15], v111 offset:36752
	s_waitcnt lgkmcnt(1)
	v_pk_fma_f32 v[18:19], v[80:81], v[2:3], v[28:29] op_sel_hi:[0,1,1]
	v_pk_fma_f32 v[16:17], v[80:81], v[0:1], v[60:61] op_sel_hi:[0,1,1]
	s_waitcnt lgkmcnt(0)
	v_pk_fma_f32 v[12:13], v[80:81], v[12:13], v[62:63] op_sel_hi:[0,1,1]
	v_pk_fma_f32 v[14:15], v[80:81], v[14:15], v[30:31] op_sel_hi:[0,1,1]
	global_store_dwordx4 v[78:79], v[16:19], off offset:384 nt
	global_store_dwordx4 v[78:79], v[12:15], off offset:400 nt
	v_mfma_f32_16x16x32_bf16 v[0:3], v[48:51], v[44:47], v[32:35]
	s_waitcnt vmcnt(14)
	v_cvt_pk_bf16_f32 v78, v52, v53
	v_or_b32_e32 v12, 16, v106
	v_or_b32_e32 v13, v12, v107
	v_lshl_add_u32 v13, v13, 5, 0
	v_lshlrev_b32_e32 v168, 9, v12
	ds_read_b128 v[72:75], v13 offset:16384
	ds_read_b128 v[68:71], v13 offset:16400
	v_lshl_add_u64 v[12:13], v[84:85], 0, v[168:169]
	v_lshl_add_u64 v[12:13], v[12:13], 0, v[92:93]
	v_lshl_add_u64 v[16:17], v[12:13], 0, s[2:3]
	v_add_co_u32_e32 v12, vcc, s75, v12
	v_cvt_pk_bf16_f32 v79, v54, v55
	s_nop 0
	v_addc_co_u32_e32 v13, vcc, 0, v13, vcc
	global_load_dwordx4 v[60:63], v[12:13], off nt
	global_load_dwordx4 v[64:67], v[16:17], off offset:16 nt
	global_load_dwordx4 v[44:47], v[16:17], off offset:144 nt
	global_load_dwordx4 v[48:51], v[16:17], off offset:128 nt
	global_load_dwordx4 v[28:31], v[16:17], off offset:272 nt
	global_load_dwordx4 v[32:35], v[16:17], off offset:256 nt
	global_load_dwordx4 v[12:15], v[16:17], off offset:400 nt
	s_nop 0
	global_load_dwordx4 v[16:19], v[16:17], off offset:384 nt
	ds_read_b128 v[80:83], v112 offset:40448
	ds_read_b128 v[114:117], v111 offset:32768
	ds_read_b128 v[118:121], v111 offset:32784
	s_waitcnt lgkmcnt(4)
	v_mov_b32_e32 v96, v75
	v_lshl_add_u64 v[98:99], v[94:95], 0, v[168:169]
	s_waitcnt lgkmcnt(1)
	v_pk_mul_f32 v[86:87], v[72:73], v[116:117] op_sel_hi:[0,1]
	v_pk_mul_f32 v[100:101], v[72:73], v[114:115] op_sel_hi:[0,1]
	v_pk_fma_f32 v[86:87], v[90:91], v[58:59], v[86:87] op_sel_hi:[0,1,1]
	v_pk_fma_f32 v[100:101], v[90:91], v[56:57], v[100:101] op_sel_hi:[0,1,1]
	s_waitcnt lgkmcnt(0)
	v_pk_mul_f32 v[56:57], v[72:73], v[120:121] op_sel_hi:[0,1]
	v_pk_mul_f32 v[58:59], v[72:73], v[118:119] op_sel_hi:[0,1]
	v_pk_fma_f32 v[114:115], v[90:91], v[54:55], v[56:57] op_sel_hi:[0,1,1]
	v_pk_fma_f32 v[116:117], v[90:91], v[52:53], v[58:59] op_sel_hi:[0,1,1]
	ds_read_b128 v[52:55], v111 offset:33280
	ds_read_b128 v[56:59], v111 offset:33296
	s_waitcnt lgkmcnt(1)
	v_pk_fma_f32 v[86:87], v[72:73], v[54:55], v[86:87] op_sel:[1,0,0]
	v_pk_fma_f32 v[100:101], v[72:73], v[52:53], v[100:101] op_sel:[1,0,0]
	s_waitcnt lgkmcnt(0)
	v_pk_fma_f32 v[114:115], v[72:73], v[58:59], v[114:115] op_sel:[1,0,0]
	v_pk_fma_f32 v[116:117], v[72:73], v[56:57], v[116:117] op_sel:[1,0,0]
	ds_read_b128 v[52:55], v111 offset:33792
	ds_read_b128 v[56:59], v111 offset:33808
	s_waitcnt lgkmcnt(1)
	v_pk_fma_f32 v[86:87], v[74:75], v[54:55], v[86:87] op_sel_hi:[0,1,1]
	v_pk_fma_f32 v[100:101], v[74:75], v[52:53], v[100:101] op_sel_hi:[0,1,1]
	s_waitcnt lgkmcnt(0)
	v_pk_fma_f32 v[114:115], v[74:75], v[58:59], v[114:115] op_sel_hi:[0,1,1]
	v_pk_fma_f32 v[116:117], v[74:75], v[56:57], v[116:117] op_sel_hi:[0,1,1]
	ds_read_b128 v[52:55], v111 offset:34304
	ds_read_b128 v[56:59], v111 offset:34320
	s_waitcnt lgkmcnt(1)
	v_pk_fma_f32 v[86:87], v[96:97], v[54:55], v[86:87] op_sel_hi:[0,1,1]
	v_pk_fma_f32 v[100:101], v[96:97], v[52:53], v[100:101] op_sel_hi:[0,1,1]
	s_waitcnt lgkmcnt(0)
	v_pk_fma_f32 v[114:115], v[96:97], v[58:59], v[114:115] op_sel_hi:[0,1,1]
	v_pk_fma_f32 v[116:117], v[96:97], v[56:57], v[116:117] op_sel_hi:[0,1,1]
	ds_read_b128 v[52:55], v111 offset:34816
	ds_read_b128 v[56:59], v111 offset:34832
	s_waitcnt lgkmcnt(1)
	v_pk_fma_f32 v[86:87], v[68:69], v[54:55], v[86:87] op_sel_hi:[0,1,1]
	v_pk_fma_f32 v[100:101], v[68:69], v[52:53], v[100:101] op_sel_hi:[0,1,1]
	s_waitcnt lgkmcnt(0)
	v_pk_fma_f32 v[114:115], v[68:69], v[58:59], v[114:115] op_sel_hi:[0,1,1]
	v_pk_fma_f32 v[116:117], v[68:69], v[56:57], v[116:117] op_sel_hi:[0,1,1]
	ds_read_b128 v[52:55], v111 offset:35328
	ds_read_b128 v[56:59], v111 offset:35344
	s_waitcnt lgkmcnt(1)
	v_pk_fma_f32 v[86:87], v[68:69], v[54:55], v[86:87] op_sel:[1,0,0]
	v_pk_fma_f32 v[100:101], v[68:69], v[52:53], v[100:101] op_sel:[1,0,0]
	s_waitcnt lgkmcnt(0)
	v_pk_fma_f32 v[114:115], v[68:69], v[58:59], v[114:115] op_sel:[1,0,0]
	v_pk_fma_f32 v[116:117], v[68:69], v[56:57], v[116:117] op_sel:[1,0,0]
	ds_read_b128 v[52:55], v111 offset:35840
	ds_read_b128 v[56:59], v111 offset:35856
	s_waitcnt lgkmcnt(1)
	v_pk_fma_f32 v[118:119], v[70:71], v[54:55], v[86:87] op_sel_hi:[0,1,1]
	v_pk_fma_f32 v[100:101], v[70:71], v[52:53], v[100:101] op_sel_hi:[0,1,1]
	s_waitcnt lgkmcnt(0)
	v_pk_fma_f32 v[120:121], v[70:71], v[58:59], v[114:115] op_sel_hi:[0,1,1]
	v_pk_fma_f32 v[122:123], v[70:71], v[56:57], v[116:117] op_sel_hi:[0,1,1]
	ds_read_b128 v[52:55], v111 offset:36352
	ds_read_b128 v[56:59], v111 offset:36368
	v_mov_b32_e32 v86, v71
	s_waitcnt lgkmcnt(1)
	v_pk_fma_f32 v[116:117], v[86:87], v[54:55], v[118:119] op_sel_hi:[0,1,1]
	v_pk_fma_f32 v[114:115], v[86:87], v[52:53], v[100:101] op_sel_hi:[0,1,1]
	v_mfma_f32_16x16x32_bf16 v[52:55], v[80:83], v[76:79], 0
	v_lshl_add_u64 v[80:81], v[98:99], 0, v[92:93]
	s_waitcnt lgkmcnt(0)
	v_pk_fma_f32 v[58:59], v[86:87], v[58:59], v[120:121] op_sel_hi:[0,1,1]
	v_pk_fma_f32 v[56:57], v[86:87], v[56:57], v[122:123] op_sel_hi:[0,1,1]
	global_store_dwordx4 v[80:81], v[114:117], off nt
	global_store_dwordx4 v[80:81], v[56:59], off offset:16 nt
	ds_read_b128 v[76:79], v112 offset:40512
	ds_read_b128 v[98:101], v111 offset:32896
	ds_read_b128 v[114:117], v111 offset:32912
	s_waitcnt vmcnt(22)
	v_cvt_pk_bf16_f32 v56, v40, v41
	v_cvt_pk_bf16_f32 v57, v42, v43
	v_cvt_pk_bf16_f32 v58, v36, v37
	s_waitcnt lgkmcnt(1)
	v_pk_mul_f32 v[82:83], v[72:73], v[100:101] op_sel_hi:[0,1]
	v_pk_mul_f32 v[98:99], v[72:73], v[98:99] op_sel_hi:[0,1]
	v_pk_fma_f32 v[82:83], v[90:91], v[42:43], v[82:83] op_sel_hi:[0,1,1]
	v_pk_fma_f32 v[98:99], v[90:91], v[40:41], v[98:99] op_sel_hi:[0,1,1]
	s_waitcnt lgkmcnt(0)
	v_pk_mul_f32 v[40:41], v[72:73], v[116:117] op_sel_hi:[0,1]
	v_pk_mul_f32 v[42:43], v[72:73], v[114:115] op_sel_hi:[0,1]
	v_cvt_pk_bf16_f32 v59, v38, v39
	v_pk_fma_f32 v[100:101], v[90:91], v[38:39], v[40:41] op_sel_hi:[0,1,1]
	v_pk_fma_f32 v[114:115], v[90:91], v[36:37], v[42:43] op_sel_hi:[0,1,1]
	ds_read_b128 v[36:39], v111 offset:33408
	ds_read_b128 v[40:43], v111 offset:33424
	s_waitcnt lgkmcnt(1)
	v_pk_fma_f32 v[82:83], v[72:73], v[38:39], v[82:83] op_sel:[1,0,0]
	v_pk_fma_f32 v[98:99], v[72:73], v[36:37], v[98:99] op_sel:[1,0,0]
	s_waitcnt lgkmcnt(0)
	v_pk_fma_f32 v[100:101], v[72:73], v[42:43], v[100:101] op_sel:[1,0,0]
	v_pk_fma_f32 v[114:115], v[72:73], v[40:41], v[114:115] op_sel:[1,0,0]
	ds_read_b128 v[36:39], v111 offset:33920
	ds_read_b128 v[40:43], v111 offset:33936
	s_waitcnt lgkmcnt(1)
	v_pk_fma_f32 v[82:83], v[74:75], v[38:39], v[82:83] op_sel_hi:[0,1,1]
	v_pk_fma_f32 v[98:99], v[74:75], v[36:37], v[98:99] op_sel_hi:[0,1,1]
	s_waitcnt lgkmcnt(0)
	v_pk_fma_f32 v[100:101], v[74:75], v[42:43], v[100:101] op_sel_hi:[0,1,1]
	v_pk_fma_f32 v[114:115], v[74:75], v[40:41], v[114:115] op_sel_hi:[0,1,1]
	ds_read_b128 v[36:39], v111 offset:34432
	ds_read_b128 v[40:43], v111 offset:34448
	s_waitcnt lgkmcnt(1)
	v_pk_fma_f32 v[82:83], v[96:97], v[38:39], v[82:83] op_sel_hi:[0,1,1]
	v_pk_fma_f32 v[98:99], v[96:97], v[36:37], v[98:99] op_sel_hi:[0,1,1]
	s_waitcnt lgkmcnt(0)
	v_pk_fma_f32 v[100:101], v[96:97], v[42:43], v[100:101] op_sel_hi:[0,1,1]
	v_pk_fma_f32 v[114:115], v[96:97], v[40:41], v[114:115] op_sel_hi:[0,1,1]
	ds_read_b128 v[36:39], v111 offset:34944
	ds_read_b128 v[40:43], v111 offset:34960
	s_waitcnt lgkmcnt(1)
	v_pk_fma_f32 v[82:83], v[68:69], v[38:39], v[82:83] op_sel_hi:[0,1,1]
	v_pk_fma_f32 v[98:99], v[68:69], v[36:37], v[98:99] op_sel_hi:[0,1,1]
	s_waitcnt lgkmcnt(0)
	v_pk_fma_f32 v[100:101], v[68:69], v[42:43], v[100:101] op_sel_hi:[0,1,1]
	v_pk_fma_f32 v[114:115], v[68:69], v[40:41], v[114:115] op_sel_hi:[0,1,1]
	ds_read_b128 v[36:39], v111 offset:35456
	ds_read_b128 v[40:43], v111 offset:35472
	s_waitcnt lgkmcnt(1)
	v_pk_fma_f32 v[82:83], v[68:69], v[38:39], v[82:83] op_sel:[1,0,0]
	v_pk_fma_f32 v[98:99], v[68:69], v[36:37], v[98:99] op_sel:[1,0,0]
	s_waitcnt lgkmcnt(0)
	v_pk_fma_f32 v[100:101], v[68:69], v[42:43], v[100:101] op_sel:[1,0,0]
	v_pk_fma_f32 v[114:115], v[68:69], v[40:41], v[114:115] op_sel:[1,0,0]
	ds_read_b128 v[36:39], v111 offset:35968
	ds_read_b128 v[40:43], v111 offset:35984
	s_waitcnt lgkmcnt(1)
	v_pk_fma_f32 v[82:83], v[70:71], v[38:39], v[82:83] op_sel_hi:[0,1,1]
	v_pk_fma_f32 v[98:99], v[70:71], v[36:37], v[98:99] op_sel_hi:[0,1,1]
	s_waitcnt lgkmcnt(0)
	v_pk_fma_f32 v[116:117], v[70:71], v[42:43], v[100:101] op_sel_hi:[0,1,1]
	v_pk_fma_f32 v[114:115], v[70:71], v[40:41], v[114:115] op_sel_hi:[0,1,1]
	ds_read_b128 v[36:39], v111 offset:36480
	ds_read_b128 v[40:43], v111 offset:36496
	s_waitcnt lgkmcnt(1)
	v_pk_fma_f32 v[100:101], v[86:87], v[38:39], v[82:83] op_sel_hi:[0,1,1]
	v_pk_fma_f32 v[98:99], v[86:87], v[36:37], v[98:99] op_sel_hi:[0,1,1]
	s_waitcnt lgkmcnt(0)
	v_pk_fma_f32 v[42:43], v[86:87], v[42:43], v[116:117] op_sel_hi:[0,1,1]
	v_pk_fma_f32 v[40:41], v[86:87], v[40:41], v[114:115] op_sel_hi:[0,1,1]
	global_store_dwordx4 v[80:81], v[98:101], off offset:128 nt
	global_store_dwordx4 v[80:81], v[40:43], off offset:144 nt
	v_mfma_f32_16x16x32_bf16 v[36:39], v[76:79], v[56:59], v[52:55]
	s_nop 2
	ds_read_b128 v[52:55], v112 offset:40576
	ds_read_b128 v[56:59], v111 offset:33024
	ds_read_b128 v[76:79], v111 offset:33040
	s_waitcnt vmcnt(22)
	v_cvt_pk_bf16_f32 v40, v24, v25
	v_cvt_pk_bf16_f32 v41, v26, v27
	v_cvt_pk_bf16_f32 v42, v20, v21
	s_waitcnt lgkmcnt(1)
	v_pk_mul_f32 v[58:59], v[72:73], v[58:59] op_sel_hi:[0,1]
	v_pk_mul_f32 v[56:57], v[72:73], v[56:57] op_sel_hi:[0,1]
	v_pk_fma_f32 v[58:59], v[90:91], v[26:27], v[58:59] op_sel_hi:[0,1,1]
	v_pk_fma_f32 v[56:57], v[90:91], v[24:25], v[56:57] op_sel_hi:[0,1,1]
	s_waitcnt lgkmcnt(0)
	v_pk_mul_f32 v[24:25], v[72:73], v[78:79] op_sel_hi:[0,1]
	v_pk_mul_f32 v[26:27], v[72:73], v[76:77] op_sel_hi:[0,1]
	v_cvt_pk_bf16_f32 v43, v22, v23
	v_pk_fma_f32 v[76:77], v[90:91], v[22:23], v[24:25] op_sel_hi:[0,1,1]
	v_pk_fma_f32 v[78:79], v[90:91], v[20:21], v[26:27] op_sel_hi:[0,1,1]
	ds_read_b128 v[20:23], v111 offset:33536
	ds_read_b128 v[24:27], v111 offset:33552
	s_waitcnt vmcnt(10)
	v_cvt_pk_bf16_f32 v82, v64, v65
	v_cvt_pk_bf16_f32 v83, v66, v67
	s_waitcnt lgkmcnt(1)
	v_pk_fma_f32 v[58:59], v[72:73], v[22:23], v[58:59] op_sel:[1,0,0]
	v_pk_fma_f32 v[56:57], v[72:73], v[20:21], v[56:57] op_sel:[1,0,0]
	s_waitcnt lgkmcnt(0)
	v_pk_fma_f32 v[76:77], v[72:73], v[26:27], v[76:77] op_sel:[1,0,0]
	v_pk_fma_f32 v[78:79], v[72:73], v[24:25], v[78:79] op_sel:[1,0,0]
	ds_read_b128 v[20:23], v111 offset:34048
	ds_read_b128 v[24:27], v111 offset:34064
	s_waitcnt lgkmcnt(1)
	v_pk_fma_f32 v[58:59], v[74:75], v[22:23], v[58:59] op_sel_hi:[0,1,1]
	v_pk_fma_f32 v[56:57], v[74:75], v[20:21], v[56:57] op_sel_hi:[0,1,1]
	s_waitcnt lgkmcnt(0)
	v_pk_fma_f32 v[76:77], v[74:75], v[26:27], v[76:77] op_sel_hi:[0,1,1]
	v_pk_fma_f32 v[78:79], v[74:75], v[24:25], v[78:79] op_sel_hi:[0,1,1]
	ds_read_b128 v[20:23], v111 offset:34560
	ds_read_b128 v[24:27], v111 offset:34576
	s_waitcnt lgkmcnt(1)
	v_pk_fma_f32 v[58:59], v[96:97], v[22:23], v[58:59] op_sel_hi:[0,1,1]
	v_pk_fma_f32 v[56:57], v[96:97], v[20:21], v[56:57] op_sel_hi:[0,1,1]
	s_waitcnt lgkmcnt(0)
	v_pk_fma_f32 v[76:77], v[96:97], v[26:27], v[76:77] op_sel_hi:[0,1,1]
	v_pk_fma_f32 v[78:79], v[96:97], v[24:25], v[78:79] op_sel_hi:[0,1,1]
	ds_read_b128 v[20:23], v111 offset:35072
	ds_read_b128 v[24:27], v111 offset:35088
	s_waitcnt lgkmcnt(1)
	v_pk_fma_f32 v[58:59], v[68:69], v[22:23], v[58:59] op_sel_hi:[0,1,1]
	v_pk_fma_f32 v[56:57], v[68:69], v[20:21], v[56:57] op_sel_hi:[0,1,1]
	s_waitcnt lgkmcnt(0)
	v_pk_fma_f32 v[76:77], v[68:69], v[26:27], v[76:77] op_sel_hi:[0,1,1]
	v_pk_fma_f32 v[78:79], v[68:69], v[24:25], v[78:79] op_sel_hi:[0,1,1]
	ds_read_b128 v[20:23], v111 offset:35584
	ds_read_b128 v[24:27], v111 offset:35600
	s_waitcnt lgkmcnt(1)
	v_pk_fma_f32 v[58:59], v[68:69], v[22:23], v[58:59] op_sel:[1,0,0]
	v_pk_fma_f32 v[56:57], v[68:69], v[20:21], v[56:57] op_sel:[1,0,0]
	s_waitcnt lgkmcnt(0)
	v_pk_fma_f32 v[76:77], v[68:69], v[26:27], v[76:77] op_sel:[1,0,0]
	v_pk_fma_f32 v[78:79], v[68:69], v[24:25], v[78:79] op_sel:[1,0,0]
	ds_read_b128 v[20:23], v111 offset:36096
	ds_read_b128 v[24:27], v111 offset:36112
	s_waitcnt lgkmcnt(1)
	v_pk_fma_f32 v[58:59], v[70:71], v[22:23], v[58:59] op_sel_hi:[0,1,1]
	v_pk_fma_f32 v[56:57], v[70:71], v[20:21], v[56:57] op_sel_hi:[0,1,1]
	s_waitcnt lgkmcnt(0)
	v_pk_fma_f32 v[76:77], v[70:71], v[26:27], v[76:77] op_sel_hi:[0,1,1]
	v_pk_fma_f32 v[78:79], v[70:71], v[24:25], v[78:79] op_sel_hi:[0,1,1]
	ds_read_b128 v[20:23], v111 offset:36608
	ds_read_b128 v[24:27], v111 offset:36624
	s_waitcnt lgkmcnt(1)
	v_pk_fma_f32 v[58:59], v[86:87], v[22:23], v[58:59] op_sel_hi:[0,1,1]
	v_pk_fma_f32 v[56:57], v[86:87], v[20:21], v[56:57] op_sel_hi:[0,1,1]
	s_waitcnt lgkmcnt(0)
	v_pk_fma_f32 v[26:27], v[86:87], v[26:27], v[76:77] op_sel_hi:[0,1,1]
	v_pk_fma_f32 v[24:25], v[86:87], v[24:25], v[78:79] op_sel_hi:[0,1,1]
	global_store_dwordx4 v[80:81], v[56:59], off offset:256 nt
	global_store_dwordx4 v[80:81], v[24:27], off offset:272 nt
	v_mfma_f32_16x16x32_bf16 v[20:23], v[52:55], v[40:43], v[36:39]
	s_nop 2
	ds_read_b128 v[36:39], v112 offset:40640
	ds_read_b128 v[40:43], v111 offset:33152
	ds_read_b128 v[52:55], v111 offset:33168
	v_cvt_pk_bf16_f32 v24, v8, v9
	v_cvt_pk_bf16_f32 v25, v10, v11
	v_cvt_pk_bf16_f32 v26, v4, v5
	s_waitcnt lgkmcnt(1)
	v_pk_mul_f32 v[42:43], v[72:73], v[42:43] op_sel_hi:[0,1]
	v_pk_mul_f32 v[40:41], v[72:73], v[40:41] op_sel_hi:[0,1]
	v_pk_fma_f32 v[42:43], v[90:91], v[10:11], v[42:43] op_sel_hi:[0,1,1]
	v_pk_fma_f32 v[40:41], v[90:91], v[8:9], v[40:41] op_sel_hi:[0,1,1]
	s_waitcnt lgkmcnt(0)
	v_pk_mul_f32 v[8:9], v[72:73], v[54:55] op_sel_hi:[0,1]
	v_pk_mul_f32 v[10:11], v[72:73], v[52:53] op_sel_hi:[0,1]
	v_cvt_pk_bf16_f32 v27, v6, v7
	v_pk_fma_f32 v[52:53], v[90:91], v[6:7], v[8:9] op_sel_hi:[0,1,1]
	v_pk_fma_f32 v[54:55], v[90:91], v[4:5], v[10:11] op_sel_hi:[0,1,1]
	ds_read_b128 v[4:7], v111 offset:33664
	ds_read_b128 v[8:11], v111 offset:33680
	s_waitcnt lgkmcnt(1)
	v_pk_fma_f32 v[42:43], v[72:73], v[6:7], v[42:43] op_sel:[1,0,0]
	v_pk_fma_f32 v[40:41], v[72:73], v[4:5], v[40:41] op_sel:[1,0,0]
	s_waitcnt lgkmcnt(0)
	v_pk_fma_f32 v[52:53], v[72:73], v[10:11], v[52:53] op_sel:[1,0,0]
	v_pk_fma_f32 v[54:55], v[72:73], v[8:9], v[54:55] op_sel:[1,0,0]
	ds_read_b128 v[4:7], v111 offset:34176
	ds_read_b128 v[8:11], v111 offset:34192
	s_waitcnt lgkmcnt(1)
	v_pk_fma_f32 v[42:43], v[74:75], v[6:7], v[42:43] op_sel_hi:[0,1,1]
	v_pk_fma_f32 v[40:41], v[74:75], v[4:5], v[40:41] op_sel_hi:[0,1,1]
	s_waitcnt lgkmcnt(0)
	v_pk_fma_f32 v[52:53], v[74:75], v[10:11], v[52:53] op_sel_hi:[0,1,1]
	v_pk_fma_f32 v[54:55], v[74:75], v[8:9], v[54:55] op_sel_hi:[0,1,1]
	ds_read_b128 v[4:7], v111 offset:34688
	ds_read_b128 v[8:11], v111 offset:34704
	s_waitcnt lgkmcnt(1)
	v_pk_fma_f32 v[42:43], v[96:97], v[6:7], v[42:43] op_sel_hi:[0,1,1]
	v_pk_fma_f32 v[40:41], v[96:97], v[4:5], v[40:41] op_sel_hi:[0,1,1]
	s_waitcnt lgkmcnt(0)
	v_pk_fma_f32 v[52:53], v[96:97], v[10:11], v[52:53] op_sel_hi:[0,1,1]
	v_pk_fma_f32 v[54:55], v[96:97], v[8:9], v[54:55] op_sel_hi:[0,1,1]
	ds_read_b128 v[4:7], v111 offset:35200
	ds_read_b128 v[8:11], v111 offset:35216
	s_waitcnt lgkmcnt(1)
	v_pk_fma_f32 v[42:43], v[68:69], v[6:7], v[42:43] op_sel_hi:[0,1,1]
	v_pk_fma_f32 v[40:41], v[68:69], v[4:5], v[40:41] op_sel_hi:[0,1,1]
	s_waitcnt lgkmcnt(0)
	v_pk_fma_f32 v[52:53], v[68:69], v[10:11], v[52:53] op_sel_hi:[0,1,1]
	v_pk_fma_f32 v[54:55], v[68:69], v[8:9], v[54:55] op_sel_hi:[0,1,1]
	ds_read_b128 v[4:7], v111 offset:35712
	ds_read_b128 v[8:11], v111 offset:35728
	s_waitcnt lgkmcnt(1)
	v_pk_fma_f32 v[42:43], v[68:69], v[6:7], v[42:43] op_sel:[1,0,0]
	v_pk_fma_f32 v[40:41], v[68:69], v[4:5], v[40:41] op_sel:[1,0,0]
	s_waitcnt lgkmcnt(0)
	v_pk_fma_f32 v[52:53], v[68:69], v[10:11], v[52:53] op_sel:[1,0,0]
	v_pk_fma_f32 v[54:55], v[68:69], v[8:9], v[54:55] op_sel:[1,0,0]
	ds_read_b128 v[4:7], v111 offset:36224
	ds_read_b128 v[8:11], v111 offset:36240
	s_waitcnt lgkmcnt(1)
	v_pk_fma_f32 v[42:43], v[70:71], v[6:7], v[42:43] op_sel_hi:[0,1,1]
	v_pk_fma_f32 v[40:41], v[70:71], v[4:5], v[40:41] op_sel_hi:[0,1,1]
	s_waitcnt lgkmcnt(0)
	v_pk_fma_f32 v[52:53], v[70:71], v[10:11], v[52:53] op_sel_hi:[0,1,1]
	v_pk_fma_f32 v[54:55], v[70:71], v[8:9], v[54:55] op_sel_hi:[0,1,1]
	ds_read_b128 v[4:7], v111 offset:36736
	ds_read_b128 v[8:11], v111 offset:36752
	s_waitcnt lgkmcnt(1)
	v_pk_fma_f32 v[42:43], v[86:87], v[6:7], v[42:43] op_sel_hi:[0,1,1]
	v_pk_fma_f32 v[40:41], v[86:87], v[4:5], v[40:41] op_sel_hi:[0,1,1]
	v_mfma_f32_16x16x32_bf16 v[4:7], v[36:39], v[24:27], v[20:23]
	s_waitcnt lgkmcnt(0)
	v_pk_fma_f32 v[8:9], v[86:87], v[8:9], v[54:55] op_sel_hi:[0,1,1]
	v_pk_fma_f32 v[10:11], v[86:87], v[10:11], v[52:53] op_sel_hi:[0,1,1]
	global_store_dwordx4 v[80:81], v[40:43], off offset:384 nt
	global_store_dwordx4 v[80:81], v[8:11], off offset:400 nt
	v_or_b32_e32 v20, 32, v106
	v_lshlrev_b32_e32 v168, 9, v20
	v_or_b32_e32 v8, v20, v107
	v_lshl_add_u64 v[20:21], v[84:85], 0, v[168:169]
	v_lshl_add_u64 v[20:21], v[20:21], 0, v[92:93]
	v_lshl_add_u64 v[24:25], v[20:21], 0, s[2:3]
	v_add_co_u32_e32 v20, vcc, s75, v20
	v_lshl_add_u32 v8, v8, 5, 0
	s_nop 0
	v_addc_co_u32_e32 v21, vcc, 0, v21, vcc
	ds_read_b128 v[76:79], v8 offset:16384
	ds_read_b128 v[8:11], v8 offset:16400
	global_load_dwordx4 v[68:71], v[20:21], off nt
	global_load_dwordx4 v[72:75], v[24:25], off offset:16 nt
	global_load_dwordx4 v[52:55], v[24:25], off offset:144 nt
	global_load_dwordx4 v[56:59], v[24:25], off offset:128 nt
	global_load_dwordx4 v[36:39], v[24:25], off offset:272 nt
	global_load_dwordx4 v[40:43], v[24:25], off offset:256 nt
	global_load_dwordx4 v[20:23], v[24:25], off offset:400 nt
	s_nop 0
	global_load_dwordx4 v[24:27], v[24:25], off offset:384 nt
	ds_read_b128 v[84:87], v112 offset:40448
	ds_read_b128 v[114:117], v111 offset:32768
	ds_read_b128 v[118:121], v111 offset:32784
	v_cvt_pk_bf16_f32 v80, v60, v61
	v_cvt_pk_bf16_f32 v81, v62, v63
	v_lshl_add_u64 v[100:101], v[94:95], 0, v[168:169]
	s_waitcnt lgkmcnt(1)
	v_pk_mul_f32 v[98:99], v[76:77], v[116:117] op_sel_hi:[0,1]
	v_pk_mul_f32 v[114:115], v[76:77], v[114:115] op_sel_hi:[0,1]
	v_pk_fma_f32 v[98:99], v[90:91], v[62:63], v[98:99] op_sel_hi:[0,1,1]
	v_pk_fma_f32 v[114:115], v[90:91], v[60:61], v[114:115] op_sel_hi:[0,1,1]
	s_waitcnt lgkmcnt(0)
	v_pk_mul_f32 v[60:61], v[76:77], v[120:121] op_sel_hi:[0,1]
	v_pk_mul_f32 v[62:63], v[76:77], v[118:119] op_sel_hi:[0,1]
	v_pk_fma_f32 v[116:117], v[90:91], v[66:67], v[60:61] op_sel_hi:[0,1,1]
	v_pk_fma_f32 v[118:119], v[90:91], v[64:65], v[62:63] op_sel_hi:[0,1,1]
	ds_read_b128 v[60:63], v111 offset:33280
	ds_read_b128 v[64:67], v111 offset:33296
	v_mov_b32_e32 v96, v11
	v_cmp_eq_u32_e64 s[2:3], 0, v106
	s_waitcnt lgkmcnt(1)
	v_pk_fma_f32 v[98:99], v[76:77], v[62:63], v[98:99] op_sel:[1,0,0]
	v_pk_fma_f32 v[114:115], v[76:77], v[60:61], v[114:115] op_sel:[1,0,0]
	s_waitcnt lgkmcnt(0)
	v_pk_fma_f32 v[116:117], v[76:77], v[66:67], v[116:117] op_sel:[1,0,0]
	v_pk_fma_f32 v[118:119], v[76:77], v[64:65], v[118:119] op_sel:[1,0,0]
	ds_read_b128 v[60:63], v111 offset:33792
	ds_read_b128 v[64:67], v111 offset:33808
	s_waitcnt lgkmcnt(1)
	v_pk_fma_f32 v[120:121], v[78:79], v[62:63], v[98:99] op_sel_hi:[0,1,1]
	v_pk_fma_f32 v[114:115], v[78:79], v[60:61], v[114:115] op_sel_hi:[0,1,1]
	s_waitcnt lgkmcnt(0)
	v_pk_fma_f32 v[116:117], v[78:79], v[66:67], v[116:117] op_sel_hi:[0,1,1]
	v_pk_fma_f32 v[118:119], v[78:79], v[64:65], v[118:119] op_sel_hi:[0,1,1]
	ds_read_b128 v[60:63], v111 offset:34304
	ds_read_b128 v[64:67], v111 offset:34320
	v_mov_b32_e32 v98, v79
	s_waitcnt lgkmcnt(1)
	v_pk_fma_f32 v[120:121], v[98:99], v[62:63], v[120:121] op_sel_hi:[0,1,1]
	v_pk_fma_f32 v[114:115], v[98:99], v[60:61], v[114:115] op_sel_hi:[0,1,1]
	s_waitcnt lgkmcnt(0)
	v_pk_fma_f32 v[116:117], v[98:99], v[66:67], v[116:117] op_sel_hi:[0,1,1]
	v_pk_fma_f32 v[118:119], v[98:99], v[64:65], v[118:119] op_sel_hi:[0,1,1]
	ds_read_b128 v[60:63], v111 offset:34816
	ds_read_b128 v[64:67], v111 offset:34832
	s_waitcnt lgkmcnt(1)
	v_pk_fma_f32 v[120:121], v[8:9], v[62:63], v[120:121] op_sel_hi:[0,1,1]
	v_pk_fma_f32 v[114:115], v[8:9], v[60:61], v[114:115] op_sel_hi:[0,1,1]
	s_waitcnt lgkmcnt(0)
	v_pk_fma_f32 v[116:117], v[8:9], v[66:67], v[116:117] op_sel_hi:[0,1,1]
	v_pk_fma_f32 v[118:119], v[8:9], v[64:65], v[118:119] op_sel_hi:[0,1,1]
	ds_read_b128 v[60:63], v111 offset:35328
	ds_read_b128 v[64:67], v111 offset:35344
	s_waitcnt lgkmcnt(1)
	v_pk_fma_f32 v[120:121], v[8:9], v[62:63], v[120:121] op_sel:[1,0,0]
	v_pk_fma_f32 v[114:115], v[8:9], v[60:61], v[114:115] op_sel:[1,0,0]
	s_waitcnt lgkmcnt(0)
	v_pk_fma_f32 v[116:117], v[8:9], v[66:67], v[116:117] op_sel:[1,0,0]
	v_pk_fma_f32 v[118:119], v[8:9], v[64:65], v[118:119] op_sel:[1,0,0]
	ds_read_b128 v[60:63], v111 offset:35840
	ds_read_b128 v[64:67], v111 offset:35856
	s_waitcnt lgkmcnt(1)
	v_pk_fma_f32 v[120:121], v[10:11], v[62:63], v[120:121] op_sel_hi:[0,1,1]
	v_pk_fma_f32 v[114:115], v[10:11], v[60:61], v[114:115] op_sel_hi:[0,1,1]
	s_waitcnt lgkmcnt(0)
	v_pk_fma_f32 v[122:123], v[10:11], v[66:67], v[116:117] op_sel_hi:[0,1,1]
	v_pk_fma_f32 v[118:119], v[10:11], v[64:65], v[118:119] op_sel_hi:[0,1,1]
	ds_read_b128 v[60:63], v111 offset:36352
	ds_read_b128 v[64:67], v111 offset:36368
	s_waitcnt lgkmcnt(1)
	v_pk_fma_f32 v[116:117], v[96:97], v[62:63], v[120:121] op_sel_hi:[0,1,1]
	v_pk_fma_f32 v[114:115], v[96:97], v[60:61], v[114:115] op_sel_hi:[0,1,1]
	v_mfma_f32_16x16x32_bf16 v[60:63], v[84:87], v[80:83], 0
	v_lshl_add_u64 v[84:85], v[100:101], 0, v[92:93]
	s_waitcnt lgkmcnt(0)
	v_pk_fma_f32 v[66:67], v[96:97], v[66:67], v[122:123] op_sel_hi:[0,1,1]
	v_pk_fma_f32 v[64:65], v[96:97], v[64:65], v[118:119] op_sel_hi:[0,1,1]
	global_store_dwordx4 v[84:85], v[114:117], off nt
	global_store_dwordx4 v[84:85], v[64:67], off offset:16 nt
	ds_read_b128 v[80:83], v112 offset:40512
	ds_read_b128 v[114:117], v111 offset:32896
	ds_read_b128 v[118:121], v111 offset:32912
	s_waitcnt vmcnt(22)
	v_cvt_pk_bf16_f32 v64, v48, v49
	v_cvt_pk_bf16_f32 v65, v50, v51
	v_cvt_pk_bf16_f32 v66, v44, v45
	s_waitcnt lgkmcnt(1)
	v_pk_mul_f32 v[86:87], v[76:77], v[116:117] op_sel_hi:[0,1]
	v_pk_mul_f32 v[100:101], v[76:77], v[114:115] op_sel_hi:[0,1]
	v_pk_fma_f32 v[86:87], v[90:91], v[50:51], v[86:87] op_sel_hi:[0,1,1]
	v_pk_fma_f32 v[100:101], v[90:91], v[48:49], v[100:101] op_sel_hi:[0,1,1]
	s_waitcnt lgkmcnt(0)
	v_pk_mul_f32 v[48:49], v[76:77], v[120:121] op_sel_hi:[0,1]
	v_pk_mul_f32 v[50:51], v[76:77], v[118:119] op_sel_hi:[0,1]
	v_cvt_pk_bf16_f32 v67, v46, v47
	v_pk_fma_f32 v[114:115], v[90:91], v[46:47], v[48:49] op_sel_hi:[0,1,1]
	v_pk_fma_f32 v[116:117], v[90:91], v[44:45], v[50:51] op_sel_hi:[0,1,1]
	ds_read_b128 v[44:47], v111 offset:33408
	ds_read_b128 v[48:51], v111 offset:33424
	s_waitcnt lgkmcnt(1)
	v_pk_fma_f32 v[86:87], v[76:77], v[46:47], v[86:87] op_sel:[1,0,0]
	v_pk_fma_f32 v[100:101], v[76:77], v[44:45], v[100:101] op_sel:[1,0,0]
	s_waitcnt lgkmcnt(0)
	v_pk_fma_f32 v[114:115], v[76:77], v[50:51], v[114:115] op_sel:[1,0,0]
	v_pk_fma_f32 v[116:117], v[76:77], v[48:49], v[116:117] op_sel:[1,0,0]
	ds_read_b128 v[44:47], v111 offset:33920
	ds_read_b128 v[48:51], v111 offset:33936
	s_waitcnt lgkmcnt(1)
	v_pk_fma_f32 v[86:87], v[78:79], v[46:47], v[86:87] op_sel_hi:[0,1,1]
	v_pk_fma_f32 v[100:101], v[78:79], v[44:45], v[100:101] op_sel_hi:[0,1,1]
	s_waitcnt lgkmcnt(0)
	v_pk_fma_f32 v[114:115], v[78:79], v[50:51], v[114:115] op_sel_hi:[0,1,1]
	v_pk_fma_f32 v[116:117], v[78:79], v[48:49], v[116:117] op_sel_hi:[0,1,1]
	ds_read_b128 v[44:47], v111 offset:34432
	ds_read_b128 v[48:51], v111 offset:34448
	s_waitcnt lgkmcnt(1)
	v_pk_fma_f32 v[86:87], v[98:99], v[46:47], v[86:87] op_sel_hi:[0,1,1]
	v_pk_fma_f32 v[100:101], v[98:99], v[44:45], v[100:101] op_sel_hi:[0,1,1]
	s_waitcnt lgkmcnt(0)
	v_pk_fma_f32 v[114:115], v[98:99], v[50:51], v[114:115] op_sel_hi:[0,1,1]
	v_pk_fma_f32 v[116:117], v[98:99], v[48:49], v[116:117] op_sel_hi:[0,1,1]
	ds_read_b128 v[44:47], v111 offset:34944
	ds_read_b128 v[48:51], v111 offset:34960
	s_waitcnt lgkmcnt(1)
	v_pk_fma_f32 v[86:87], v[8:9], v[46:47], v[86:87] op_sel_hi:[0,1,1]
	v_pk_fma_f32 v[100:101], v[8:9], v[44:45], v[100:101] op_sel_hi:[0,1,1]
	s_waitcnt lgkmcnt(0)
	v_pk_fma_f32 v[114:115], v[8:9], v[50:51], v[114:115] op_sel_hi:[0,1,1]
	v_pk_fma_f32 v[116:117], v[8:9], v[48:49], v[116:117] op_sel_hi:[0,1,1]
	ds_read_b128 v[44:47], v111 offset:35456
	ds_read_b128 v[48:51], v111 offset:35472
	s_waitcnt lgkmcnt(1)
	v_pk_fma_f32 v[86:87], v[8:9], v[46:47], v[86:87] op_sel:[1,0,0]
	v_pk_fma_f32 v[100:101], v[8:9], v[44:45], v[100:101] op_sel:[1,0,0]
	s_waitcnt lgkmcnt(0)
	v_pk_fma_f32 v[114:115], v[8:9], v[50:51], v[114:115] op_sel:[1,0,0]
	v_pk_fma_f32 v[116:117], v[8:9], v[48:49], v[116:117] op_sel:[1,0,0]
	ds_read_b128 v[44:47], v111 offset:35968
	ds_read_b128 v[48:51], v111 offset:35984
	s_waitcnt lgkmcnt(1)
	v_pk_fma_f32 v[86:87], v[10:11], v[46:47], v[86:87] op_sel_hi:[0,1,1]
	v_pk_fma_f32 v[100:101], v[10:11], v[44:45], v[100:101] op_sel_hi:[0,1,1]
	s_waitcnt lgkmcnt(0)
	v_pk_fma_f32 v[118:119], v[10:11], v[50:51], v[114:115] op_sel_hi:[0,1,1]
	v_pk_fma_f32 v[120:121], v[10:11], v[48:49], v[116:117] op_sel_hi:[0,1,1]
	ds_read_b128 v[44:47], v111 offset:36480
	ds_read_b128 v[48:51], v111 offset:36496
	s_waitcnt lgkmcnt(1)
	v_pk_fma_f32 v[116:117], v[96:97], v[46:47], v[86:87] op_sel_hi:[0,1,1]
	v_pk_fma_f32 v[114:115], v[96:97], v[44:45], v[100:101] op_sel_hi:[0,1,1]
	s_waitcnt lgkmcnt(0)
	v_pk_fma_f32 v[50:51], v[96:97], v[50:51], v[118:119] op_sel_hi:[0,1,1]
	v_pk_fma_f32 v[48:49], v[96:97], v[48:49], v[120:121] op_sel_hi:[0,1,1]
	global_store_dwordx4 v[84:85], v[114:117], off offset:128 nt
	global_store_dwordx4 v[84:85], v[48:51], off offset:144 nt
	v_mfma_f32_16x16x32_bf16 v[44:47], v[80:83], v[64:67], v[60:63]
	s_nop 2
	ds_read_b128 v[60:63], v112 offset:40576
	ds_read_b128 v[64:67], v111 offset:33024
	ds_read_b128 v[80:83], v111 offset:33040
	s_waitcnt vmcnt(22)
	v_cvt_pk_bf16_f32 v48, v32, v33
	v_cvt_pk_bf16_f32 v49, v34, v35
	v_cvt_pk_bf16_f32 v50, v28, v29
	s_waitcnt lgkmcnt(1)
	v_pk_mul_f32 v[66:67], v[76:77], v[66:67] op_sel_hi:[0,1]
	v_pk_mul_f32 v[64:65], v[76:77], v[64:65] op_sel_hi:[0,1]
	v_pk_fma_f32 v[66:67], v[90:91], v[34:35], v[66:67] op_sel_hi:[0,1,1]
	v_pk_fma_f32 v[64:65], v[90:91], v[32:33], v[64:65] op_sel_hi:[0,1,1]
	s_waitcnt lgkmcnt(0)
	v_pk_mul_f32 v[32:33], v[76:77], v[82:83] op_sel_hi:[0,1]
	v_pk_mul_f32 v[34:35], v[76:77], v[80:81] op_sel_hi:[0,1]
	v_cvt_pk_bf16_f32 v51, v30, v31
	v_pk_fma_f32 v[80:81], v[90:91], v[30:31], v[32:33] op_sel_hi:[0,1,1]
	v_pk_fma_f32 v[82:83], v[90:91], v[28:29], v[34:35] op_sel_hi:[0,1,1]
	ds_read_b128 v[28:31], v111 offset:33536
	ds_read_b128 v[32:35], v111 offset:33552
	s_waitcnt lgkmcnt(1)
	v_pk_fma_f32 v[66:67], v[76:77], v[30:31], v[66:67] op_sel:[1,0,0]
	v_pk_fma_f32 v[64:65], v[76:77], v[28:29], v[64:65] op_sel:[1,0,0]
	s_waitcnt lgkmcnt(0)
	v_pk_fma_f32 v[80:81], v[76:77], v[34:35], v[80:81] op_sel:[1,0,0]
	v_pk_fma_f32 v[82:83], v[76:77], v[32:33], v[82:83] op_sel:[1,0,0]
	ds_read_b128 v[28:31], v111 offset:34048
	ds_read_b128 v[32:35], v111 offset:34064
	s_waitcnt lgkmcnt(1)
	v_pk_fma_f32 v[66:67], v[78:79], v[30:31], v[66:67] op_sel_hi:[0,1,1]
	v_pk_fma_f32 v[64:65], v[78:79], v[28:29], v[64:65] op_sel_hi:[0,1,1]
	s_waitcnt lgkmcnt(0)
	v_pk_fma_f32 v[80:81], v[78:79], v[34:35], v[80:81] op_sel_hi:[0,1,1]
	v_pk_fma_f32 v[82:83], v[78:79], v[32:33], v[82:83] op_sel_hi:[0,1,1]
	ds_read_b128 v[28:31], v111 offset:34560
	ds_read_b128 v[32:35], v111 offset:34576
	s_waitcnt lgkmcnt(1)
	v_pk_fma_f32 v[66:67], v[98:99], v[30:31], v[66:67] op_sel_hi:[0,1,1]
	v_pk_fma_f32 v[64:65], v[98:99], v[28:29], v[64:65] op_sel_hi:[0,1,1]
	s_waitcnt lgkmcnt(0)
	v_pk_fma_f32 v[80:81], v[98:99], v[34:35], v[80:81] op_sel_hi:[0,1,1]
	v_pk_fma_f32 v[82:83], v[98:99], v[32:33], v[82:83] op_sel_hi:[0,1,1]
	ds_read_b128 v[28:31], v111 offset:35072
	ds_read_b128 v[32:35], v111 offset:35088
	s_waitcnt lgkmcnt(1)
	v_pk_fma_f32 v[66:67], v[8:9], v[30:31], v[66:67] op_sel_hi:[0,1,1]
	v_pk_fma_f32 v[64:65], v[8:9], v[28:29], v[64:65] op_sel_hi:[0,1,1]
	s_waitcnt lgkmcnt(0)
	v_pk_fma_f32 v[80:81], v[8:9], v[34:35], v[80:81] op_sel_hi:[0,1,1]
	v_pk_fma_f32 v[82:83], v[8:9], v[32:33], v[82:83] op_sel_hi:[0,1,1]
	ds_read_b128 v[28:31], v111 offset:35584
	ds_read_b128 v[32:35], v111 offset:35600
	s_waitcnt lgkmcnt(1)
	v_pk_fma_f32 v[66:67], v[8:9], v[30:31], v[66:67] op_sel:[1,0,0]
	v_pk_fma_f32 v[64:65], v[8:9], v[28:29], v[64:65] op_sel:[1,0,0]
	s_waitcnt lgkmcnt(0)
	v_pk_fma_f32 v[80:81], v[8:9], v[34:35], v[80:81] op_sel:[1,0,0]
	v_pk_fma_f32 v[82:83], v[8:9], v[32:33], v[82:83] op_sel:[1,0,0]
	ds_read_b128 v[28:31], v111 offset:36096
	ds_read_b128 v[32:35], v111 offset:36112
	s_waitcnt lgkmcnt(1)
	v_pk_fma_f32 v[66:67], v[10:11], v[30:31], v[66:67] op_sel_hi:[0,1,1]
	v_pk_fma_f32 v[64:65], v[10:11], v[28:29], v[64:65] op_sel_hi:[0,1,1]
	s_waitcnt lgkmcnt(0)
	v_pk_fma_f32 v[80:81], v[10:11], v[34:35], v[80:81] op_sel_hi:[0,1,1]
	v_pk_fma_f32 v[82:83], v[10:11], v[32:33], v[82:83] op_sel_hi:[0,1,1]
	ds_read_b128 v[28:31], v111 offset:36608
	ds_read_b128 v[32:35], v111 offset:36624
	s_waitcnt lgkmcnt(1)
	v_pk_fma_f32 v[66:67], v[96:97], v[30:31], v[66:67] op_sel_hi:[0,1,1]
	v_pk_fma_f32 v[64:65], v[96:97], v[28:29], v[64:65] op_sel_hi:[0,1,1]
	s_waitcnt lgkmcnt(0)
	v_pk_fma_f32 v[34:35], v[96:97], v[34:35], v[80:81] op_sel_hi:[0,1,1]
	v_pk_fma_f32 v[32:33], v[96:97], v[32:33], v[82:83] op_sel_hi:[0,1,1]
	global_store_dwordx4 v[84:85], v[64:67], off offset:256 nt
	global_store_dwordx4 v[84:85], v[32:35], off offset:272 nt
	v_mfma_f32_16x16x32_bf16 v[28:31], v[60:63], v[48:51], v[44:47]
	s_nop 2
	ds_read_b128 v[44:47], v112 offset:40640
	ds_read_b128 v[48:51], v111 offset:33152
	ds_read_b128 v[60:63], v111 offset:33168
	s_waitcnt vmcnt(22)
	v_cvt_pk_bf16_f32 v32, v16, v17
	v_cvt_pk_bf16_f32 v33, v18, v19
	v_cvt_pk_bf16_f32 v34, v12, v13
	s_waitcnt lgkmcnt(1)
	v_pk_mul_f32 v[50:51], v[76:77], v[50:51] op_sel_hi:[0,1]
	v_pk_mul_f32 v[48:49], v[76:77], v[48:49] op_sel_hi:[0,1]
	v_pk_fma_f32 v[50:51], v[90:91], v[18:19], v[50:51] op_sel_hi:[0,1,1]
	v_pk_fma_f32 v[48:49], v[90:91], v[16:17], v[48:49] op_sel_hi:[0,1,1]
	s_waitcnt lgkmcnt(0)
	v_pk_mul_f32 v[16:17], v[76:77], v[62:63] op_sel_hi:[0,1]
	v_pk_mul_f32 v[18:19], v[76:77], v[60:61] op_sel_hi:[0,1]
	v_cvt_pk_bf16_f32 v35, v14, v15
	v_pk_fma_f32 v[60:61], v[90:91], v[14:15], v[16:17] op_sel_hi:[0,1,1]
	v_pk_fma_f32 v[62:63], v[90:91], v[12:13], v[18:19] op_sel_hi:[0,1,1]
	ds_read_b128 v[12:15], v111 offset:33664
	ds_read_b128 v[16:19], v111 offset:33680
	s_waitcnt lgkmcnt(1)
	v_pk_fma_f32 v[50:51], v[76:77], v[14:15], v[50:51] op_sel:[1,0,0]
	v_pk_fma_f32 v[48:49], v[76:77], v[12:13], v[48:49] op_sel:[1,0,0]
	s_waitcnt lgkmcnt(0)
	v_pk_fma_f32 v[60:61], v[76:77], v[18:19], v[60:61] op_sel:[1,0,0]
	v_pk_fma_f32 v[62:63], v[76:77], v[16:17], v[62:63] op_sel:[1,0,0]
	ds_read_b128 v[12:15], v111 offset:34176
	ds_read_b128 v[16:19], v111 offset:34192
	s_waitcnt lgkmcnt(1)
	v_pk_fma_f32 v[50:51], v[78:79], v[14:15], v[50:51] op_sel_hi:[0,1,1]
	v_pk_fma_f32 v[48:49], v[78:79], v[12:13], v[48:49] op_sel_hi:[0,1,1]
	s_waitcnt lgkmcnt(0)
	v_pk_fma_f32 v[60:61], v[78:79], v[18:19], v[60:61] op_sel_hi:[0,1,1]
	v_pk_fma_f32 v[62:63], v[78:79], v[16:17], v[62:63] op_sel_hi:[0,1,1]
	ds_read_b128 v[12:15], v111 offset:34688
	ds_read_b128 v[16:19], v111 offset:34704
	s_waitcnt lgkmcnt(1)
	v_pk_fma_f32 v[50:51], v[98:99], v[14:15], v[50:51] op_sel_hi:[0,1,1]
	v_pk_fma_f32 v[48:49], v[98:99], v[12:13], v[48:49] op_sel_hi:[0,1,1]
	s_waitcnt lgkmcnt(0)
	v_pk_fma_f32 v[60:61], v[98:99], v[18:19], v[60:61] op_sel_hi:[0,1,1]
	v_pk_fma_f32 v[62:63], v[98:99], v[16:17], v[62:63] op_sel_hi:[0,1,1]
	ds_read_b128 v[12:15], v111 offset:35200
	ds_read_b128 v[16:19], v111 offset:35216
	s_waitcnt lgkmcnt(1)
	v_pk_fma_f32 v[50:51], v[8:9], v[14:15], v[50:51] op_sel_hi:[0,1,1]
	v_pk_fma_f32 v[48:49], v[8:9], v[12:13], v[48:49] op_sel_hi:[0,1,1]
	s_waitcnt lgkmcnt(0)
	v_pk_fma_f32 v[60:61], v[8:9], v[18:19], v[60:61] op_sel_hi:[0,1,1]
	v_pk_fma_f32 v[62:63], v[8:9], v[16:17], v[62:63] op_sel_hi:[0,1,1]
	ds_read_b128 v[12:15], v111 offset:35712
	ds_read_b128 v[16:19], v111 offset:35728
	s_waitcnt lgkmcnt(1)
	v_pk_fma_f32 v[50:51], v[8:9], v[14:15], v[50:51] op_sel:[1,0,0]
	v_pk_fma_f32 v[48:49], v[8:9], v[12:13], v[48:49] op_sel:[1,0,0]
	s_waitcnt lgkmcnt(0)
	v_pk_fma_f32 v[60:61], v[8:9], v[18:19], v[60:61] op_sel:[1,0,0]
	v_pk_fma_f32 v[8:9], v[8:9], v[16:17], v[62:63] op_sel:[1,0,0]
	ds_read_b128 v[12:15], v111 offset:36224
	ds_read_b128 v[16:19], v111 offset:36240
	s_waitcnt lgkmcnt(1)
	v_pk_fma_f32 v[50:51], v[10:11], v[14:15], v[50:51] op_sel_hi:[0,1,1]
	v_pk_fma_f32 v[48:49], v[10:11], v[12:13], v[48:49] op_sel_hi:[0,1,1]
	s_waitcnt lgkmcnt(0)
	v_pk_fma_f32 v[60:61], v[10:11], v[18:19], v[60:61] op_sel_hi:[0,1,1]
	v_pk_fma_f32 v[62:63], v[10:11], v[16:17], v[8:9] op_sel_hi:[0,1,1]
	ds_read_b128 v[8:11], v111 offset:36736
	ds_read_b128 v[12:15], v111 offset:36752
	s_waitcnt lgkmcnt(1)
	v_pk_fma_f32 v[18:19], v[96:97], v[10:11], v[50:51] op_sel_hi:[0,1,1]
	v_pk_fma_f32 v[16:17], v[96:97], v[8:9], v[48:49] op_sel_hi:[0,1,1]
	s_waitcnt lgkmcnt(0)
	v_pk_fma_f32 v[12:13], v[96:97], v[12:13], v[62:63] op_sel_hi:[0,1,1]
	v_mfma_f32_16x16x32_bf16 v[8:11], v[44:47], v[32:35], v[28:31]
	v_fma_f32 v14, v96, v14, v60
	v_fma_f32 v15, v96, v15, v61
	global_store_dwordx4 v[84:85], v[16:19], off offset:384 nt
	global_store_dwordx4 v[84:85], v[12:15], off offset:400 nt
	v_or_b32_e32 v28, 48, v106
	v_lshlrev_b32_e32 v168, 9, v28
	v_or_b32_e32 v12, v28, v107
	v_lshl_add_u32 v12, v12, 5, 0
	ds_read_b128 v[16:19], v12 offset:16384
	ds_read_b128 v[12:15], v12 offset:16400
	ds_read_b128 v[32:35], v112 offset:40448
	ds_read_b128 v[46:49], v111 offset:32768
	ds_read_b128 v[60:63], v111 offset:32784
	s_waitcnt vmcnt(15)
	v_cvt_pk_bf16_f32 v28, v68, v69
	v_cvt_pk_bf16_f32 v29, v70, v71
	s_waitcnt vmcnt(14)
	v_cvt_pk_bf16_f32 v30, v72, v73
	s_waitcnt lgkmcnt(1)
	v_pk_mul_f32 v[48:49], v[16:17], v[48:49] op_sel_hi:[0,1]
	v_pk_mul_f32 v[46:47], v[16:17], v[46:47] op_sel_hi:[0,1]
	v_pk_fma_f32 v[50:51], v[90:91], v[70:71], v[48:49] op_sel_hi:[0,1,1]
	v_pk_fma_f32 v[64:65], v[90:91], v[68:69], v[46:47] op_sel_hi:[0,1,1]
	s_waitcnt lgkmcnt(0)
	v_pk_mul_f32 v[46:47], v[16:17], v[62:63] op_sel_hi:[0,1]
	v_pk_mul_f32 v[48:49], v[16:17], v[60:61] op_sel_hi:[0,1]
	v_pk_fma_f32 v[66:67], v[90:91], v[74:75], v[46:47] op_sel_hi:[0,1,1]
	v_pk_fma_f32 v[68:69], v[90:91], v[72:73], v[48:49] op_sel_hi:[0,1,1]
	ds_read_b128 v[46:49], v111 offset:33280
	ds_read_b128 v[60:63], v111 offset:33296
	v_cvt_pk_bf16_f32 v31, v74, v75
	v_lshl_add_u64 v[44:45], v[94:95], 0, v[168:169]
	s_waitcnt lgkmcnt(1)
	v_pk_fma_f32 v[50:51], v[16:17], v[48:49], v[50:51] op_sel:[1,0,0]
	v_pk_fma_f32 v[64:65], v[16:17], v[46:47], v[64:65] op_sel:[1,0,0]
	s_waitcnt lgkmcnt(0)
	v_pk_fma_f32 v[66:67], v[16:17], v[62:63], v[66:67] op_sel:[1,0,0]
	v_pk_fma_f32 v[68:69], v[16:17], v[60:61], v[68:69] op_sel:[1,0,0]
	ds_read_b128 v[46:49], v111 offset:33792
	ds_read_b128 v[60:63], v111 offset:33808
	v_mfma_f32_16x16x32_bf16 v[28:31], v[32:35], v[28:31], 0
	s_waitcnt vmcnt(12)
	v_cvt_pk_bf16_f32 v32, v56, v57
	v_cvt_pk_bf16_f32 v33, v58, v59
	s_waitcnt lgkmcnt(1)
	v_pk_fma_f32 v[50:51], v[18:19], v[48:49], v[50:51] op_sel_hi:[0,1,1]
	v_pk_fma_f32 v[70:71], v[18:19], v[46:47], v[64:65] op_sel_hi:[0,1,1]
	s_waitcnt lgkmcnt(0)
	v_pk_fma_f32 v[66:67], v[18:19], v[62:63], v[66:67] op_sel_hi:[0,1,1]
	ds_read_b128 v[46:49], v111 offset:34304
	ds_read_b128 v[62:65], v111 offset:34320
	v_pk_fma_f32 v[68:69], v[18:19], v[60:61], v[68:69] op_sel_hi:[0,1,1]
	v_mov_b32_e32 v60, v19
	v_cvt_pk_bf16_f32 v34, v52, v53
	s_waitcnt lgkmcnt(1)
	v_pk_fma_f32 v[50:51], v[60:61], v[48:49], v[50:51] op_sel_hi:[0,1,1]
	v_pk_fma_f32 v[70:71], v[60:61], v[46:47], v[70:71] op_sel_hi:[0,1,1]
	s_waitcnt lgkmcnt(0)
	v_pk_fma_f32 v[66:67], v[60:61], v[64:65], v[66:67] op_sel_hi:[0,1,1]
	v_pk_fma_f32 v[68:69], v[60:61], v[62:63], v[68:69] op_sel_hi:[0,1,1]
	ds_read_b128 v[46:49], v111 offset:34816
	ds_read_b128 v[62:65], v111 offset:34832
	v_cvt_pk_bf16_f32 v35, v54, v55
	s_waitcnt lgkmcnt(1)
	v_pk_fma_f32 v[50:51], v[12:13], v[48:49], v[50:51] op_sel_hi:[0,1,1]
	v_pk_fma_f32 v[70:71], v[12:13], v[46:47], v[70:71] op_sel_hi:[0,1,1]
	s_waitcnt lgkmcnt(0)
	v_pk_fma_f32 v[66:67], v[12:13], v[64:65], v[66:67] op_sel_hi:[0,1,1]
	v_pk_fma_f32 v[68:69], v[12:13], v[62:63], v[68:69] op_sel_hi:[0,1,1]
	ds_read_b128 v[46:49], v111 offset:35328
	ds_read_b128 v[62:65], v111 offset:35344
	s_waitcnt lgkmcnt(1)
	v_pk_fma_f32 v[50:51], v[12:13], v[48:49], v[50:51] op_sel:[1,0,0]
	v_pk_fma_f32 v[70:71], v[12:13], v[46:47], v[70:71] op_sel:[1,0,0]
	s_waitcnt lgkmcnt(0)
	v_pk_fma_f32 v[66:67], v[12:13], v[64:65], v[66:67] op_sel:[1,0,0]
	v_pk_fma_f32 v[68:69], v[12:13], v[62:63], v[68:69] op_sel:[1,0,0]
	ds_read_b128 v[46:49], v111 offset:35840
	ds_read_b128 v[62:65], v111 offset:35856
	s_waitcnt lgkmcnt(1)
	v_pk_fma_f32 v[72:73], v[14:15], v[48:49], v[50:51] op_sel_hi:[0,1,1]
	v_pk_fma_f32 v[70:71], v[14:15], v[46:47], v[70:71] op_sel_hi:[0,1,1]
	s_waitcnt lgkmcnt(0)
	v_pk_fma_f32 v[74:75], v[14:15], v[64:65], v[66:67] op_sel_hi:[0,1,1]
	v_pk_fma_f32 v[76:77], v[14:15], v[62:63], v[68:69] op_sel_hi:[0,1,1]
	ds_read_b128 v[46:49], v111 offset:36352
	ds_read_b128 v[62:65], v111 offset:36368
	v_mov_b32_e32 v50, v15
	s_waitcnt lgkmcnt(1)
	v_pk_fma_f32 v[68:69], v[50:51], v[48:49], v[72:73] op_sel_hi:[0,1,1]
	v_pk_fma_f32 v[66:67], v[50:51], v[46:47], v[70:71] op_sel_hi:[0,1,1]
	v_lshl_add_u64 v[48:49], v[44:45], 0, v[92:93]
	s_waitcnt lgkmcnt(0)
	v_pk_fma_f32 v[64:65], v[50:51], v[64:65], v[74:75] op_sel_hi:[0,1,1]
	v_pk_fma_f32 v[62:63], v[50:51], v[62:63], v[76:77] op_sel_hi:[0,1,1]
	global_store_dwordx4 v[48:49], v[66:69], off nt
	global_store_dwordx4 v[48:49], v[62:65], off offset:16 nt
	ds_read_b128 v[44:47], v112 offset:40512
	ds_read_b128 v[62:65], v111 offset:32896
	ds_read_b128 v[66:69], v111 offset:32912
	s_waitcnt lgkmcnt(2)
	v_mfma_f32_16x16x32_bf16 v[28:31], v[44:47], v[32:35], v[28:31]
	s_waitcnt lgkmcnt(1)
	v_pk_mul_f32 v[64:65], v[16:17], v[64:65] op_sel_hi:[0,1]
	v_pk_mul_f32 v[62:63], v[16:17], v[62:63] op_sel_hi:[0,1]
	v_pk_fma_f32 v[64:65], v[90:91], v[58:59], v[64:65] op_sel_hi:[0,1,1]
	v_pk_fma_f32 v[62:63], v[90:91], v[56:57], v[62:63] op_sel_hi:[0,1,1]
	s_waitcnt lgkmcnt(0)
	v_pk_mul_f32 v[56:57], v[16:17], v[68:69] op_sel_hi:[0,1]
	v_pk_mul_f32 v[58:59], v[16:17], v[66:67] op_sel_hi:[0,1]
	v_pk_fma_f32 v[66:67], v[90:91], v[54:55], v[56:57] op_sel_hi:[0,1,1]
	v_pk_fma_f32 v[68:69], v[90:91], v[52:53], v[58:59] op_sel_hi:[0,1,1]
	ds_read_b128 v[52:55], v111 offset:33408
	ds_read_b128 v[56:59], v111 offset:33424
	s_waitcnt vmcnt(12)
	v_cvt_pk_bf16_f32 v32, v40, v41
	v_cvt_pk_bf16_f32 v33, v42, v43
	v_cvt_pk_bf16_f32 v34, v36, v37
	s_waitcnt lgkmcnt(1)
	v_pk_fma_f32 v[64:65], v[16:17], v[54:55], v[64:65] op_sel:[1,0,0]
	v_pk_fma_f32 v[62:63], v[16:17], v[52:53], v[62:63] op_sel:[1,0,0]
	s_waitcnt lgkmcnt(0)
	v_pk_fma_f32 v[66:67], v[16:17], v[58:59], v[66:67] op_sel:[1,0,0]
	v_pk_fma_f32 v[68:69], v[16:17], v[56:57], v[68:69] op_sel:[1,0,0]
	ds_read_b128 v[52:55], v111 offset:33920
	ds_read_b128 v[56:59], v111 offset:33936
	v_cvt_pk_bf16_f32 v35, v38, v39
	s_waitcnt lgkmcnt(1)
	v_pk_fma_f32 v[64:65], v[18:19], v[54:55], v[64:65] op_sel_hi:[0,1,1]
	v_pk_fma_f32 v[62:63], v[18:19], v[52:53], v[62:63] op_sel_hi:[0,1,1]
	s_waitcnt lgkmcnt(0)
	v_pk_fma_f32 v[66:67], v[18:19], v[58:59], v[66:67] op_sel_hi:[0,1,1]
	v_pk_fma_f32 v[68:69], v[18:19], v[56:57], v[68:69] op_sel_hi:[0,1,1]
	ds_read_b128 v[52:55], v111 offset:34432
	ds_read_b128 v[56:59], v111 offset:34448
	s_waitcnt lgkmcnt(1)
	v_pk_fma_f32 v[64:65], v[60:61], v[54:55], v[64:65] op_sel_hi:[0,1,1]
	v_pk_fma_f32 v[62:63], v[60:61], v[52:53], v[62:63] op_sel_hi:[0,1,1]
	s_waitcnt lgkmcnt(0)
	v_pk_fma_f32 v[66:67], v[60:61], v[58:59], v[66:67] op_sel_hi:[0,1,1]
	v_pk_fma_f32 v[68:69], v[60:61], v[56:57], v[68:69] op_sel_hi:[0,1,1]
	ds_read_b128 v[52:55], v111 offset:34944
	ds_read_b128 v[56:59], v111 offset:34960
	s_waitcnt lgkmcnt(1)
	v_pk_fma_f32 v[64:65], v[12:13], v[54:55], v[64:65] op_sel_hi:[0,1,1]
	v_pk_fma_f32 v[62:63], v[12:13], v[52:53], v[62:63] op_sel_hi:[0,1,1]
	s_waitcnt lgkmcnt(0)
	v_pk_fma_f32 v[66:67], v[12:13], v[58:59], v[66:67] op_sel_hi:[0,1,1]
	v_pk_fma_f32 v[68:69], v[12:13], v[56:57], v[68:69] op_sel_hi:[0,1,1]
	ds_read_b128 v[52:55], v111 offset:35456
	ds_read_b128 v[56:59], v111 offset:35472
	s_waitcnt lgkmcnt(1)
	v_pk_fma_f32 v[64:65], v[12:13], v[54:55], v[64:65] op_sel:[1,0,0]
	v_pk_fma_f32 v[62:63], v[12:13], v[52:53], v[62:63] op_sel:[1,0,0]
	s_waitcnt lgkmcnt(0)
	v_pk_fma_f32 v[66:67], v[12:13], v[58:59], v[66:67] op_sel:[1,0,0]
	v_pk_fma_f32 v[68:69], v[12:13], v[56:57], v[68:69] op_sel:[1,0,0]
	ds_read_b128 v[52:55], v111 offset:35968
	ds_read_b128 v[56:59], v111 offset:35984
	s_waitcnt lgkmcnt(1)
	v_pk_fma_f32 v[64:65], v[14:15], v[54:55], v[64:65] op_sel_hi:[0,1,1]
	v_pk_fma_f32 v[62:63], v[14:15], v[52:53], v[62:63] op_sel_hi:[0,1,1]
	s_waitcnt lgkmcnt(0)
	v_pk_fma_f32 v[66:67], v[14:15], v[58:59], v[66:67] op_sel_hi:[0,1,1]
	v_pk_fma_f32 v[68:69], v[14:15], v[56:57], v[68:69] op_sel_hi:[0,1,1]
	ds_read_b128 v[52:55], v111 offset:36480
	ds_read_b128 v[56:59], v111 offset:36496
	s_waitcnt lgkmcnt(1)
	v_pk_fma_f32 v[54:55], v[50:51], v[54:55], v[64:65] op_sel_hi:[0,1,1]
	v_pk_fma_f32 v[52:53], v[50:51], v[52:53], v[62:63] op_sel_hi:[0,1,1]
	s_waitcnt lgkmcnt(0)
	v_pk_fma_f32 v[58:59], v[50:51], v[58:59], v[66:67] op_sel_hi:[0,1,1]
	v_pk_fma_f32 v[56:57], v[50:51], v[56:57], v[68:69] op_sel_hi:[0,1,1]
	global_store_dwordx4 v[48:49], v[52:55], off offset:128 nt
	global_store_dwordx4 v[48:49], v[56:59], off offset:144 nt
	ds_read_b128 v[44:47], v112 offset:40576
	ds_read_b128 v[52:55], v111 offset:33024
	ds_read_b128 v[56:59], v111 offset:33040
	s_waitcnt lgkmcnt(2)
	v_mfma_f32_16x16x32_bf16 v[28:31], v[44:47], v[32:35], v[28:31]
	s_waitcnt lgkmcnt(1)
	v_pk_mul_f32 v[54:55], v[16:17], v[54:55] op_sel_hi:[0,1]
	v_pk_mul_f32 v[52:53], v[16:17], v[52:53] op_sel_hi:[0,1]
	v_pk_fma_f32 v[54:55], v[90:91], v[42:43], v[54:55] op_sel_hi:[0,1,1]
	v_pk_fma_f32 v[52:53], v[90:91], v[40:41], v[52:53] op_sel_hi:[0,1,1]
	s_waitcnt lgkmcnt(0)
	v_pk_mul_f32 v[40:41], v[16:17], v[58:59] op_sel_hi:[0,1]
	v_pk_mul_f32 v[42:43], v[16:17], v[56:57] op_sel_hi:[0,1]
	v_pk_fma_f32 v[56:57], v[90:91], v[38:39], v[40:41] op_sel_hi:[0,1,1]
	v_pk_fma_f32 v[58:59], v[90:91], v[36:37], v[42:43] op_sel_hi:[0,1,1]
	ds_read_b128 v[36:39], v111 offset:33536
	ds_read_b128 v[40:43], v111 offset:33552
	s_waitcnt vmcnt(12)
	v_cvt_pk_bf16_f32 v32, v24, v25
	v_cvt_pk_bf16_f32 v33, v26, v27
	v_cvt_pk_bf16_f32 v34, v20, v21
	s_waitcnt lgkmcnt(1)
	v_pk_fma_f32 v[54:55], v[16:17], v[38:39], v[54:55] op_sel:[1,0,0]
	v_pk_fma_f32 v[52:53], v[16:17], v[36:37], v[52:53] op_sel:[1,0,0]
	s_waitcnt lgkmcnt(0)
	v_pk_fma_f32 v[56:57], v[16:17], v[42:43], v[56:57] op_sel:[1,0,0]
	v_pk_fma_f32 v[58:59], v[16:17], v[40:41], v[58:59] op_sel:[1,0,0]
	ds_read_b128 v[36:39], v111 offset:34048
	ds_read_b128 v[40:43], v111 offset:34064
	v_cvt_pk_bf16_f32 v35, v22, v23
	s_waitcnt lgkmcnt(1)
	v_pk_fma_f32 v[54:55], v[18:19], v[38:39], v[54:55] op_sel_hi:[0,1,1]
	v_pk_fma_f32 v[52:53], v[18:19], v[36:37], v[52:53] op_sel_hi:[0,1,1]
	s_waitcnt lgkmcnt(0)
	v_pk_fma_f32 v[56:57], v[18:19], v[42:43], v[56:57] op_sel_hi:[0,1,1]
	v_pk_fma_f32 v[58:59], v[18:19], v[40:41], v[58:59] op_sel_hi:[0,1,1]
	ds_read_b128 v[36:39], v111 offset:34560
	ds_read_b128 v[40:43], v111 offset:34576
	s_waitcnt lgkmcnt(1)
	v_pk_fma_f32 v[54:55], v[60:61], v[38:39], v[54:55] op_sel_hi:[0,1,1]
	v_pk_fma_f32 v[52:53], v[60:61], v[36:37], v[52:53] op_sel_hi:[0,1,1]
	s_waitcnt lgkmcnt(0)
	v_pk_fma_f32 v[56:57], v[60:61], v[42:43], v[56:57] op_sel_hi:[0,1,1]
	v_pk_fma_f32 v[58:59], v[60:61], v[40:41], v[58:59] op_sel_hi:[0,1,1]
	ds_read_b128 v[36:39], v111 offset:35072
	ds_read_b128 v[40:43], v111 offset:35088
	s_waitcnt lgkmcnt(1)
	v_pk_fma_f32 v[54:55], v[12:13], v[38:39], v[54:55] op_sel_hi:[0,1,1]
	v_pk_fma_f32 v[52:53], v[12:13], v[36:37], v[52:53] op_sel_hi:[0,1,1]
	s_waitcnt lgkmcnt(0)
	v_pk_fma_f32 v[56:57], v[12:13], v[42:43], v[56:57] op_sel_hi:[0,1,1]
	v_pk_fma_f32 v[58:59], v[12:13], v[40:41], v[58:59] op_sel_hi:[0,1,1]
	ds_read_b128 v[36:39], v111 offset:35584
	ds_read_b128 v[40:43], v111 offset:35600
	s_waitcnt lgkmcnt(1)
	v_pk_fma_f32 v[54:55], v[12:13], v[38:39], v[54:55] op_sel:[1,0,0]
	v_pk_fma_f32 v[52:53], v[12:13], v[36:37], v[52:53] op_sel:[1,0,0]
	s_waitcnt lgkmcnt(0)
	v_pk_fma_f32 v[56:57], v[12:13], v[42:43], v[56:57] op_sel:[1,0,0]
	v_pk_fma_f32 v[58:59], v[12:13], v[40:41], v[58:59] op_sel:[1,0,0]
	ds_read_b128 v[36:39], v111 offset:36096
	ds_read_b128 v[40:43], v111 offset:36112
	s_waitcnt lgkmcnt(1)
	v_pk_fma_f32 v[54:55], v[14:15], v[38:39], v[54:55] op_sel_hi:[0,1,1]
	v_pk_fma_f32 v[52:53], v[14:15], v[36:37], v[52:53] op_sel_hi:[0,1,1]
	s_waitcnt lgkmcnt(0)
	v_pk_fma_f32 v[56:57], v[14:15], v[42:43], v[56:57] op_sel_hi:[0,1,1]
	v_pk_fma_f32 v[58:59], v[14:15], v[40:41], v[58:59] op_sel_hi:[0,1,1]
	ds_read_b128 v[36:39], v111 offset:36608
	ds_read_b128 v[40:43], v111 offset:36624
	s_waitcnt lgkmcnt(1)
	v_pk_fma_f32 v[38:39], v[50:51], v[38:39], v[54:55] op_sel_hi:[0,1,1]
	v_pk_fma_f32 v[36:37], v[50:51], v[36:37], v[52:53] op_sel_hi:[0,1,1]
	s_waitcnt lgkmcnt(0)
	v_pk_fma_f32 v[42:43], v[50:51], v[42:43], v[56:57] op_sel_hi:[0,1,1]
	v_pk_fma_f32 v[40:41], v[50:51], v[40:41], v[58:59] op_sel_hi:[0,1,1]
	global_store_dwordx4 v[48:49], v[36:39], off offset:256 nt
	global_store_dwordx4 v[48:49], v[40:43], off offset:272 nt
	ds_read_b128 v[36:39], v112 offset:40640
	ds_read_b128 v[40:43], v111 offset:33152
	ds_read_b128 v[44:47], v111 offset:33168
	s_waitcnt lgkmcnt(1)
	v_pk_mul_f32 v[42:43], v[16:17], v[42:43] op_sel_hi:[0,1]
	v_pk_mul_f32 v[40:41], v[16:17], v[40:41] op_sel_hi:[0,1]
	v_pk_fma_f32 v[42:43], v[90:91], v[26:27], v[42:43] op_sel_hi:[0,1,1]
	v_pk_fma_f32 v[40:41], v[90:91], v[24:25], v[40:41] op_sel_hi:[0,1,1]
	s_waitcnt lgkmcnt(0)
	v_pk_mul_f32 v[24:25], v[16:17], v[46:47] op_sel_hi:[0,1]
	v_pk_mul_f32 v[26:27], v[16:17], v[44:45] op_sel_hi:[0,1]
	v_pk_fma_f32 v[44:45], v[90:91], v[22:23], v[24:25] op_sel_hi:[0,1,1]
	v_pk_fma_f32 v[46:47], v[90:91], v[20:21], v[26:27] op_sel_hi:[0,1,1]
	ds_read_b128 v[20:23], v111 offset:33664
	ds_read_b128 v[24:27], v111 offset:33680
	s_waitcnt lgkmcnt(1)
	v_pk_fma_f32 v[42:43], v[16:17], v[22:23], v[42:43] op_sel:[1,0,0]
	v_pk_fma_f32 v[40:41], v[16:17], v[20:21], v[40:41] op_sel:[1,0,0]
	s_waitcnt lgkmcnt(0)
	v_pk_fma_f32 v[44:45], v[16:17], v[26:27], v[44:45] op_sel:[1,0,0]
	v_pk_fma_f32 v[16:17], v[16:17], v[24:25], v[46:47] op_sel:[1,0,0]
	ds_read_b128 v[20:23], v111 offset:34176
	ds_read_b128 v[24:27], v111 offset:34192
	s_waitcnt lgkmcnt(1)
	v_pk_fma_f32 v[42:43], v[18:19], v[22:23], v[42:43] op_sel_hi:[0,1,1]
	v_pk_fma_f32 v[40:41], v[18:19], v[20:21], v[40:41] op_sel_hi:[0,1,1]
	s_waitcnt lgkmcnt(0)
	v_pk_fma_f32 v[26:27], v[18:19], v[26:27], v[44:45] op_sel_hi:[0,1,1]
	v_pk_fma_f32 v[24:25], v[18:19], v[24:25], v[16:17] op_sel_hi:[0,1,1]
	ds_read_b128 v[16:19], v111 offset:34688
	ds_read_b128 v[20:23], v111 offset:34704
	s_waitcnt lgkmcnt(1)
	v_pk_fma_f32 v[42:43], v[60:61], v[18:19], v[42:43] op_sel_hi:[0,1,1]
	v_pk_fma_f32 v[40:41], v[60:61], v[16:17], v[40:41] op_sel_hi:[0,1,1]
	s_waitcnt lgkmcnt(0)
	v_pk_fma_f32 v[26:27], v[60:61], v[22:23], v[26:27] op_sel_hi:[0,1,1]
	v_pk_fma_f32 v[24:25], v[60:61], v[20:21], v[24:25] op_sel_hi:[0,1,1]
	ds_read_b128 v[16:19], v111 offset:35200
	ds_read_b128 v[20:23], v111 offset:35216
	s_waitcnt lgkmcnt(1)
	v_pk_fma_f32 v[42:43], v[12:13], v[18:19], v[42:43] op_sel_hi:[0,1,1]
	v_pk_fma_f32 v[40:41], v[12:13], v[16:17], v[40:41] op_sel_hi:[0,1,1]
	s_waitcnt lgkmcnt(0)
	v_pk_fma_f32 v[26:27], v[12:13], v[22:23], v[26:27] op_sel_hi:[0,1,1]
	v_pk_fma_f32 v[24:25], v[12:13], v[20:21], v[24:25] op_sel_hi:[0,1,1]
	ds_read_b128 v[16:19], v111 offset:35712
	ds_read_b128 v[20:23], v111 offset:35728
	s_waitcnt lgkmcnt(1)
	v_pk_fma_f32 v[42:43], v[12:13], v[18:19], v[42:43] op_sel:[1,0,0]
	v_pk_fma_f32 v[40:41], v[12:13], v[16:17], v[40:41] op_sel:[1,0,0]
	s_waitcnt lgkmcnt(0)
	v_pk_fma_f32 v[26:27], v[12:13], v[22:23], v[26:27] op_sel:[1,0,0]
	v_pk_fma_f32 v[12:13], v[12:13], v[20:21], v[24:25] op_sel:[1,0,0]
	ds_read_b128 v[16:19], v111 offset:36224
	ds_read_b128 v[20:23], v111 offset:36240
	s_waitcnt lgkmcnt(1)
	v_pk_fma_f32 v[24:25], v[14:15], v[18:19], v[42:43] op_sel_hi:[0,1,1]
	v_pk_fma_f32 v[40:41], v[14:15], v[16:17], v[40:41] op_sel_hi:[0,1,1]
	s_waitcnt lgkmcnt(0)
	v_pk_fma_f32 v[26:27], v[14:15], v[22:23], v[26:27] op_sel_hi:[0,1,1]
	v_pk_fma_f32 v[42:43], v[14:15], v[20:21], v[12:13] op_sel_hi:[0,1,1]
	ds_read_b128 v[12:15], v111 offset:36736
	ds_read_b128 v[16:19], v111 offset:36752
	s_waitcnt lgkmcnt(1)
	v_pk_fma_f32 v[22:23], v[50:51], v[14:15], v[24:25] op_sel_hi:[0,1,1]
	v_pk_fma_f32 v[20:21], v[50:51], v[12:13], v[40:41] op_sel_hi:[0,1,1]
	s_waitcnt lgkmcnt(0)
	v_pk_fma_f32 v[16:17], v[50:51], v[16:17], v[42:43] op_sel_hi:[0,1,1]
	v_pk_fma_f32 v[18:19], v[50:51], v[18:19], v[26:27] op_sel_hi:[0,1,1]
	global_store_dwordx4 v[48:49], v[20:23], off offset:384 nt
	global_store_dwordx4 v[48:49], v[16:19], off offset:400 nt
	v_mfma_f32_16x16x32_bf16 v[12:15], v[36:39], v[32:35], v[28:31]
	v_and_b32_e32 v24, 0xffffffcf, v97
	v_add_u32_e32 v16, s96, v88
	v_ashrrev_i32_e32 v17, 31, v16
	v_lshl_add_u64 v[16:17], v[16:17], 2, s[36:37]
	global_load_dword v33, v[16:17], off
	v_lshrrev_b32_e32 v16, 2, v97
	v_and_b32_e32 v35, 4, v16
	v_xor_b32_e32 v16, 8, v188
	v_cmp_lt_i32_e32 vcc, v16, v110
	v_lshl_add_u32 v44, v35, 11, 0
	v_ashrrev_i32_e32 v25, 31, v24
	v_cndmask_b32_e32 v16, v188, v16, vcc
	v_lshlrev_b32_e32 v30, 2, v16
	v_or_b32_e32 v16, v109, v35
	v_lshl_add_u32 v17, v16, 2, 0
	ds_read_b32 v17, v17 offset:37120
	v_lshl_add_u32 v16, v16, 5, 0
	v_cmp_gt_u32_e32 vcc, 2, v105
	s_and_b64 s[2:3], s[2:3], vcc
	s_waitcnt lgkmcnt(0)
	v_mul_f32_e32 v17, 0x3fb8aa3b, v17
	v_exp_f32_e32 v43, v17
	v_mul_u32_u24_e32 v17, 0x1b00, v35
	v_add_lshl_u32 v168, v17, s8, 1
	v_lshlrev_b32_e32 v17, 2, v24
	v_add_u32_e32 v45, v44, v17
	ds_read2_b32 v[46:47], v45 offset1:16
	v_lshl_add_u64 v[28:29], s[6:7], 0, v[168:169]
	v_lshl_add_u64 v[26:27], v[24:25], 1, v[28:29]
	global_load_ushort v244, v[26:27], off
	v_mov_b32_e32 v250, 0x3600
	v_mov_b32_e32 v251, 0
	v_lshl_add_u64 v[248:249], v[26:27], 0, v[250:251]
	global_load_ushort v245, v[248:249], off
	v_lshl_add_u64 v[252:253], v[248:249], 0, v[250:251]
	global_load_ushort v246, v[252:253], off
	v_lshl_add_u64 v[254:255], v[252:253], 0, v[250:251]
	global_load_ushort v247, v[254:255], off
	v_add_u32_e32 v34, 0, v17
	ds_read_b128 v[20:23], v16 offset:37888
	ds_read_b128 v[16:19], v16 offset:37904
	ds_read2_b32 v[48:49], v34 offset1:16
	v_add_u32_e32 v36, 0x800, v34
	ds_read2_b32 v[50:51], v36 offset1:16
	v_add_u32_e32 v37, 0x1000, v34
	ds_read2_b32 v[52:53], v37 offset1:16
	v_add_u32_e32 v38, 0x1800, v34
	ds_read2_b32 v[54:55], v38 offset1:16
	v_add_u32_e32 v39, 0x2000, v34
	ds_read2_b32 v[56:57], v39 offset1:16
	v_add_u32_e32 v40, 0x2800, v34
	ds_read2_b32 v[58:59], v40 offset1:16
	v_add_u32_e32 v41, 0x3000, v34
	ds_read2_b32 v[60:61], v41 offset1:16
	v_add_u32_e32 v42, 0x3800, v34
	ds_read2_b32 v[62:63], v42 offset1:16
	s_waitcnt vmcnt(0) lgkmcnt(10)
	v_mul_f32_e32 v31, v33, v46
	v_fmac_f32_e32 v31, v0, v43
	global_load_ushort v0, v[26:27], off
	s_waitcnt lgkmcnt(7)
	v_fmac_f32_e32 v31, v20, v48
	s_waitcnt lgkmcnt(6)
	v_fmac_f32_e32 v31, v21, v50
	s_waitcnt lgkmcnt(5)
	v_fmac_f32_e32 v31, v22, v52
	s_waitcnt lgkmcnt(4)
	v_fmac_f32_e32 v31, v23, v54
	s_waitcnt lgkmcnt(3)
	v_fmac_f32_e32 v31, v16, v56
	s_waitcnt lgkmcnt(2)
	v_fmac_f32_e32 v31, v17, v58
	s_waitcnt lgkmcnt(1)
	v_fmac_f32_e32 v31, v18, v60
	s_waitcnt lgkmcnt(0)
	v_fmac_f32_e32 v31, v19, v62
	s_waitcnt vmcnt(0)
	v_lshlrev_b32_e32 v0, 16, v0
	v_mul_f32_e32 v32, 0xbfb8aa3b, v0
	v_exp_f32_e32 v32, v32
	s_nop 0
	v_add_f32_e32 v32, 1.0, v32
	v_rcp_f32_e32 v32, v32
	s_nop 0
	v_mul_f32_e32 v0, v32, v0
	v_mul_f32_e32 v31, v31, v0
	v_mul_f32_e32 v0, v33, v47
	v_fmac_f32_e32 v0, v4, v43
	global_load_ushort v4, v[26:27], off offset:32
	v_fmac_f32_e32 v0, v20, v49
	v_fmac_f32_e32 v0, v21, v51
	v_fmac_f32_e32 v0, v22, v53
	v_fmac_f32_e32 v0, v23, v55
	v_fmac_f32_e32 v0, v16, v57
	v_fmac_f32_e32 v0, v17, v59
	v_fmac_f32_e32 v0, v18, v61
	v_fmac_f32_e32 v0, v19, v63
	s_waitcnt vmcnt(0)
	v_lshlrev_b32_e32 v4, 16, v4
	v_mul_f32_e32 v32, 0xbfb8aa3b, v4
	v_exp_f32_e32 v32, v32
	s_nop 0
	v_add_f32_e32 v32, 1.0, v32
	v_rcp_f32_e32 v32, v32
	s_nop 0
	v_mul_f32_e32 v4, v32, v4
	v_mul_f32_e32 v32, v0, v4
	ds_read_b32 v4, v45 offset:128
	v_mul_f32_e32 v0, v32, v32
	v_fmac_f32_e32 v0, v31, v31
	s_waitcnt lgkmcnt(0)
	v_mul_f32_e32 v4, v33, v4
	v_fmac_f32_e32 v4, v8, v43
	ds_read_b32 v8, v34 offset:128
	s_waitcnt lgkmcnt(0)
	v_fmac_f32_e32 v4, v20, v8
	ds_read_b32 v8, v34 offset:2176
	s_waitcnt lgkmcnt(0)
	v_fmac_f32_e32 v4, v21, v8
	ds_read_b32 v8, v34 offset:4224
	s_waitcnt lgkmcnt(0)
	v_fmac_f32_e32 v4, v22, v8
	ds_read_b32 v8, v34 offset:6272
	s_waitcnt lgkmcnt(0)
	v_fmac_f32_e32 v4, v23, v8
	ds_read_b32 v8, v34 offset:8320
	s_waitcnt lgkmcnt(0)
	v_fmac_f32_e32 v4, v16, v8
	ds_read_b32 v8, v34 offset:10368
	s_waitcnt lgkmcnt(0)
	v_fmac_f32_e32 v4, v17, v8
	ds_read_b32 v8, v34 offset:12416
	s_waitcnt lgkmcnt(0)
	v_fmac_f32_e32 v4, v18, v8
	ds_read_b32 v8, v34 offset:14464
	s_waitcnt lgkmcnt(0)
	v_fmac_f32_e32 v4, v19, v8
	global_load_ushort v8, v[26:27], off offset:64
	s_waitcnt vmcnt(0)
	v_lshlrev_b32_e32 v8, 16, v8
	v_mul_f32_e32 v26, 0xbfb8aa3b, v8
	v_exp_f32_e32 v26, v26
	s_nop 0
	v_add_f32_e32 v26, 1.0, v26
	v_rcp_f32_e32 v26, v26
	s_nop 0
	v_mul_f32_e32 v8, v26, v8
	v_or_b32_e32 v26, 48, v97
	v_mul_f32_e32 v8, v4, v8
	v_lshlrev_b32_e32 v4, 2, v26
	v_add_u32_e32 v27, v44, v4
	ds_read_b32 v27, v27
	v_add_u32_e32 v44, 0, v4
	ds_read2st64_b32 v[46:47], v44 offset1:8
	v_fmac_f32_e32 v0, v8, v8
	s_waitcnt lgkmcnt(1)
	v_mul_f32_e32 v45, v33, v27
	v_fmac_f32_e32 v45, v12, v43
	s_waitcnt lgkmcnt(0)
	v_fmac_f32_e32 v45, v20, v46
	v_fmac_f32_e32 v45, v21, v47
	ds_read2st64_b32 v[20:21], v44 offset0:16 offset1:24
	v_ashrrev_i32_e32 v27, 31, v26
	s_waitcnt lgkmcnt(0)
	v_fmac_f32_e32 v45, v22, v20
	v_fmac_f32_e32 v45, v23, v21
	ds_read2st64_b32 v[20:21], v44 offset0:32 offset1:40
	s_waitcnt lgkmcnt(0)
	v_fmac_f32_e32 v45, v16, v20
	v_fmac_f32_e32 v45, v17, v21
	ds_read2st64_b32 v[16:17], v44 offset0:48 offset1:56
	s_waitcnt lgkmcnt(0)
	v_fmac_f32_e32 v45, v18, v16
	v_fmac_f32_e32 v45, v19, v17
	v_lshl_add_u64 v[16:17], v[26:27], 1, v[28:29]
	global_load_ushort v4, v[16:17], off
	s_waitcnt vmcnt(0)
	v_lshlrev_b32_e32 v4, 16, v4
	v_mul_f32_e32 v12, 0xbfb8aa3b, v4
	v_exp_f32_e32 v12, v12
	s_nop 0
	v_add_f32_e32 v12, 1.0, v12
	v_rcp_f32_e32 v12, v12
	s_nop 0
	v_mul_f32_e32 v4, v12, v4
	v_mul_f32_e32 v12, v45, v4
	v_fmac_f32_e32 v0, v12, v12
	ds_bpermute_b32 v4, v102, v0
	s_waitcnt lgkmcnt(0)
	v_add_f32_e32 v0, v0, v4
	ds_bpermute_b32 v4, v103, v0
	s_waitcnt lgkmcnt(0)
	v_add_f32_e32 v0, v0, v4
	ds_bpermute_b32 v4, v104, v0
	s_waitcnt lgkmcnt(0)
	v_add_f32_e32 v0, v0, v4
	ds_bpermute_b32 v4, v30, v0
	s_and_saveexec_b64 s[4:5], s[2:3]
	s_cbranch_execz .LBB0_363
	v_lshl_add_u32 v16, v35, 5, v89
	s_waitcnt lgkmcnt(0)
	v_add_f32_e32 v0, v0, v4
	ds_write_b32 v16, v0 offset:39936
